# redundant s_waitcnt lgkmcnt(0) after the pre-MFMA barrier deleted in all 16 K-loop blocks (the wait before the barrier already covers it)
# baseline (speedup 1.0000x reference)
; #define PG8_STAGE(bufoff, gbase, voff) do { _Pragma("unroll") for (int _i = 0; _i < 2; ++_i) \
;         __builtin_amdgcn_global_load_lds((const unsigned*)((const char*)(gbase) + (voff)[_i]), (PG8_LAS unsigned*)(lds + (bufoff) + ldsw + _i * 8192), 16, 0, 0); } while (0)
; #define PG8_LDA(dst, b, h) do { _Pragma("unroll") for (int m = 0; m < 4; ++m) _Pragma("unroll") for (int k = 0; k < 2; ++k) dst[m][k] = *(const PG8_LAS bf16x8*)(lds + PG8_SA(b, h) + aoff + m * 2048 + k * 1024); } while (0)
; #define PG8_LDB(dst, b, h) do { _Pragma("unroll") for (int n = 0; n < 2; ++n) _Pragma("unroll") for (int k = 0; k < 2; ++k) dst[n][k] = *(const PG8_LAS bf16x8*)(lds + PG8_SB(b, h) + boff + n * 2048 + k * 1024); } while (0)
; #define PG8_MMA(ai, bj, At, Bt) do { __builtin_amdgcn_s_setprio(1); _Pragma("unroll") for (int m = 0; m < 4; ++m) _Pragma("unroll") for (int n = 0; n < 2; ++n) _Pragma("unroll") for (int k = 0; k < 2; ++k) \
;         acc[ai][bj][m][n] = __builtin_amdgcn_mfma_f32_16x16x32_bf16(Bt[n][k], At[m][k], acc[ai][bj][m][n], 0, 0, 0); __builtin_amdgcn_s_setprio(0); } while (0)
; #define PG8_WAIT_V(n) asm volatile("s_waitcnt vmcnt(" #n ")" ::: "memory")
; #define PG8_WAIT_L(n) asm volatile("s_waitcnt lgkmcnt(" #n ")" ::: "memory")
; #define PG8_BAR __builtin_amdgcn_s_barrier()
; #define PG8_SCHED __builtin_amdgcn_sched_barrier(0)
; template <class Epi, class Sched, bool ALIGN_EPI = false, bool SP2 = false>
; __device__ __forceinline__ void gemm_phase(PG8_LAS unsigned char* lds, const Gemm g, const Sched& S, const Epi& E) {
;     ...
;             PG8_LDB(B0, 0, 0); PG8_LDB(B1, 0, 1); PG8_SCHED; PG8_LDA(At, 0, 0); PG8_STAGE(PG8_SA(1, 1), a1 + hstep, voffA);
;             PG8_WAIT_V(8); PG8_WAIT_L(0); PG8_BAR; PG8_MMA(0, 0, At, B0); PG8_MMA(0, 1, At, B1); PG8_BAR; PG8_SCHED;
;             PG8_LDA(At, 0, 1); PG8_STAGE(PG8_SB(0, 0), b2, voffB); PG8_STAGE(PG8_SB(0, 1), b2 + hstep, voffB); PG8_STAGE(PG8_SA(0, 0), a2, voffA);
;             PG8_WAIT_V(8); PG8_WAIT_L(0); PG8_BAR; PG8_MMA(1, 0, At, B0); PG8_MMA(1, 1, At, B1); PG8_BAR; PG8_SCHED;
.LBB0_366:
	ds_read_b128 v[130:133], v228
	ds_read_b128 v[134:137], v228 offset:1024
	ds_read_b128 v[138:141], v228 offset:2048
	ds_read_b128 v[170:173], v228 offset:3072
	ds_read_b128 v[174:177], v229
	ds_read_b128 v[178:181], v229 offset:1024
	ds_read_b128 v[182:185], v229 offset:2048
	ds_read_b128 v[186:189], v229 offset:3072
	s_add_u32 s12, s10, 0xfff00080
	s_addc_u32 s13, s11, -1
	s_cmp_eq_u32 s80, 60
	s_cselect_b32 s15, s0, s13
	s_cselect_b32 s14, s1, s12
	s_cselect_b32 s13, s61, s77
	s_cselect_b32 s12, s69, s71
	s_add_i32 m0, s79, 0xc000
	ds_read_b128 v[190:193], v230
	ds_read_b128 v[194:197], v230 offset:1024
	ds_read_b128 v[198:201], v230 offset:2048
	ds_read_b128 v[202:205], v230 offset:3072
	ds_read_b128 v[206:209], v230 offset:4096
	ds_read_b128 v[210:213], v230 offset:5120
	ds_read_b128 v[214:217], v230 offset:6144
	ds_read_b128 v[218:221], v230 offset:7168
	global_load_lds_dwordx4 v164, s[10:11]
	s_add_i32 m0, s79, 0xe000
	s_nop 0
	global_load_lds_dwordx4 v166, s[10:11]
	s_waitcnt vmcnt(8)
	s_waitcnt lgkmcnt(0)
	s_barrier
	v_mfma_f32_16x16x32_bf16 v[126:129], v[130:133], v[190:193], v[126:129]
	v_mfma_f32_16x16x32_bf16 v[126:129], v[134:137], v[194:197], v[126:129]
	v_mfma_f32_16x16x32_bf16 v[122:125], v[138:141], v[190:193], v[122:125]
	v_mfma_f32_16x16x32_bf16 v[122:125], v[170:173], v[194:197], v[122:125]
	v_mfma_f32_16x16x32_bf16 v[110:113], v[130:133], v[198:201], v[110:113]
	v_mfma_f32_16x16x32_bf16 v[110:113], v[134:137], v[202:205], v[110:113]
	v_mfma_f32_16x16x32_bf16 v[106:109], v[138:141], v[198:201], v[106:109]
	v_mfma_f32_16x16x32_bf16 v[106:109], v[170:173], v[202:205], v[106:109]
	v_mfma_f32_16x16x32_bf16 v[94:97], v[130:133], v[206:209], v[94:97]
	v_mfma_f32_16x16x32_bf16 v[94:97], v[134:137], v[210:213], v[94:97]
	v_mfma_f32_16x16x32_bf16 v[90:93], v[138:141], v[206:209], v[90:93]
	v_mfma_f32_16x16x32_bf16 v[90:93], v[170:173], v[210:213], v[90:93]
	v_mfma_f32_16x16x32_bf16 v[78:81], v[130:133], v[214:217], v[78:81]
	v_mfma_f32_16x16x32_bf16 v[78:81], v[134:137], v[218:221], v[78:81]
	v_mfma_f32_16x16x32_bf16 v[74:77], v[138:141], v[214:217], v[74:77]
	v_mfma_f32_16x16x32_bf16 v[74:77], v[170:173], v[218:221], v[74:77]
	v_mfma_f32_16x16x32_bf16 v[118:121], v[174:177], v[190:193], v[118:121]
	v_mfma_f32_16x16x32_bf16 v[118:121], v[178:181], v[194:197], v[118:121]
	v_mfma_f32_16x16x32_bf16 v[114:117], v[182:185], v[190:193], v[114:117]
	v_mfma_f32_16x16x32_bf16 v[114:117], v[186:189], v[194:197], v[114:117]
	v_mfma_f32_16x16x32_bf16 v[102:105], v[174:177], v[198:201], v[102:105]
	v_mfma_f32_16x16x32_bf16 v[102:105], v[178:181], v[202:205], v[102:105]
	v_mfma_f32_16x16x32_bf16 v[98:101], v[182:185], v[198:201], v[98:101]
	v_mfma_f32_16x16x32_bf16 v[98:101], v[186:189], v[202:205], v[98:101]
	v_mfma_f32_16x16x32_bf16 v[86:89], v[174:177], v[206:209], v[86:89]
	v_mfma_f32_16x16x32_bf16 v[86:89], v[178:181], v[210:213], v[86:89]
	v_mfma_f32_16x16x32_bf16 v[82:85], v[182:185], v[206:209], v[82:85]
	v_mfma_f32_16x16x32_bf16 v[82:85], v[186:189], v[210:213], v[82:85]
	v_mfma_f32_16x16x32_bf16 v[70:73], v[174:177], v[214:217], v[70:73]
	v_mfma_f32_16x16x32_bf16 v[70:73], v[178:181], v[218:221], v[70:73]
	v_mfma_f32_16x16x32_bf16 v[66:69], v[182:185], v[214:217], v[66:69]
	v_mfma_f32_16x16x32_bf16 v[66:69], v[186:189], v[218:221], v[66:69]
	s_barrier
	s_add_i32 s81, s63, s67
	s_mov_b32 m0, s81
	ds_read_b128 v[190:193], v230 offset:16384
	ds_read_b128 v[194:197], v230 offset:17408
	ds_read_b128 v[198:201], v230 offset:18432
	ds_read_b128 v[202:205], v230 offset:19456
	ds_read_b128 v[206:209], v230 offset:20480
	ds_read_b128 v[210:213], v230 offset:21504
	ds_read_b128 v[214:217], v230 offset:22528
	ds_read_b128 v[218:221], v230 offset:23552
	global_load_lds_dwordx4 v144, s[12:13]
	s_add_i32 m0, s81, 0x2000
	s_add_u32 s82, s12, 0x100000
	s_addc_u32 s83, s13, 0
	s_add_i32 s81, s94, s67
	global_load_lds_dwordx4 v148, s[12:13]
	s_mov_b32 m0, s81
	s_nop 0
	global_load_lds_dwordx4 v144, s[82:83]
	s_add_i32 m0, s81, 0x2000
	s_nop 0
	global_load_lds_dwordx4 v148, s[82:83]
	s_mov_b32 m0, s79
	s_nop 0
	global_load_lds_dwordx4 v142, s[14:15]
	s_mov_b32 m0, s88
	s_nop 0
	global_load_lds_dwordx4 v146, s[14:15]
	s_waitcnt vmcnt(8)
	s_waitcnt lgkmcnt(0)
	s_barrier
	v_mfma_f32_16x16x32_bf16 v[62:65], v[130:133], v[190:193], v[62:65]
	v_mfma_f32_16x16x32_bf16 v[62:65], v[134:137], v[194:197], v[62:65]
	v_mfma_f32_16x16x32_bf16 v[58:61], v[138:141], v[190:193], v[58:61]
	v_mfma_f32_16x16x32_bf16 v[58:61], v[170:173], v[194:197], v[58:61]
	v_mfma_f32_16x16x32_bf16 v[46:49], v[130:133], v[198:201], v[46:49]
	v_mfma_f32_16x16x32_bf16 v[46:49], v[134:137], v[202:205], v[46:49]
	v_mfma_f32_16x16x32_bf16 v[42:45], v[138:141], v[198:201], v[42:45]
	v_mfma_f32_16x16x32_bf16 v[42:45], v[170:173], v[202:205], v[42:45]
	v_mfma_f32_16x16x32_bf16 v[30:33], v[130:133], v[206:209], v[30:33]
	v_mfma_f32_16x16x32_bf16 v[30:33], v[134:137], v[210:213], v[30:33]
	v_mfma_f32_16x16x32_bf16 v[26:29], v[138:141], v[206:209], v[26:29]
	v_mfma_f32_16x16x32_bf16 v[26:29], v[170:173], v[210:213], v[26:29]
	v_mfma_f32_16x16x32_bf16 v[14:17], v[130:133], v[214:217], v[14:17]
	v_mfma_f32_16x16x32_bf16 v[14:17], v[134:137], v[218:221], v[14:17]
	v_mfma_f32_16x16x32_bf16 v[10:13], v[138:141], v[214:217], v[10:13]
	v_mfma_f32_16x16x32_bf16 v[10:13], v[170:173], v[218:221], v[10:13]
	v_mfma_f32_16x16x32_bf16 v[54:57], v[174:177], v[190:193], v[54:57]
	v_mfma_f32_16x16x32_bf16 v[54:57], v[178:181], v[194:197], v[54:57]
	v_mfma_f32_16x16x32_bf16 v[50:53], v[182:185], v[190:193], v[50:53]
	v_mfma_f32_16x16x32_bf16 v[50:53], v[186:189], v[194:197], v[50:53]
	v_mfma_f32_16x16x32_bf16 v[38:41], v[174:177], v[198:201], v[38:41]
	v_mfma_f32_16x16x32_bf16 v[38:41], v[178:181], v[202:205], v[38:41]
	v_mfma_f32_16x16x32_bf16 v[34:37], v[182:185], v[198:201], v[34:37]
	v_mfma_f32_16x16x32_bf16 v[34:37], v[186:189], v[202:205], v[34:37]
	v_mfma_f32_16x16x32_bf16 v[22:25], v[174:177], v[206:209], v[22:25]
	v_mfma_f32_16x16x32_bf16 v[22:25], v[178:181], v[210:213], v[22:25]
	v_mfma_f32_16x16x32_bf16 v[18:21], v[182:185], v[206:209], v[18:21]
	v_mfma_f32_16x16x32_bf16 v[18:21], v[186:189], v[210:213], v[18:21]
	v_mfma_f32_16x16x32_bf16 v[6:9], v[174:177], v[214:217], v[6:9]
	v_mfma_f32_16x16x32_bf16 v[6:9], v[178:181], v[218:221], v[6:9]
	v_mfma_f32_16x16x32_bf16 v[2:5], v[182:185], v[214:217], v[2:5]
	v_mfma_f32_16x16x32_bf16 v[2:5], v[186:189], v[218:221], v[2:5]
	s_barrier
; #define PG8_STAGE(bufoff, gbase, voff) do { _Pragma("unroll") for (int _i = 0; _i < 2; ++_i) \
;         __builtin_amdgcn_global_load_lds((const unsigned*)((const char*)(gbase) + (voff)[_i]), (PG8_LAS unsigned*)(lds + (bufoff) + ldsw + _i * 8192), 16, 0, 0); } while (0)
; #define PG8_LDA(dst, b, h) do { _Pragma("unroll") for (int m = 0; m < 4; ++m) _Pragma("unroll") for (int k = 0; k < 2; ++k) dst[m][k] = *(const PG8_LAS bf16x8*)(lds + PG8_SA(b, h) + aoff + m * 2048 + k * 1024); } while (0)
; #define PG8_LDB(dst, b, h) do { _Pragma("unroll") for (int n = 0; n < 2; ++n) _Pragma("unroll") for (int k = 0; k < 2; ++k) dst[n][k] = *(const PG8_LAS bf16x8*)(lds + PG8_SB(b, h) + boff + n * 2048 + k * 1024); } while (0)
; #define PG8_MMA(ai, bj, At, Bt) do { __builtin_amdgcn_s_setprio(1); _Pragma("unroll") for (int m = 0; m < 4; ++m) _Pragma("unroll") for (int n = 0; n < 2; ++n) _Pragma("unroll") for (int k = 0; k < 2; ++k) \
;         acc[ai][bj][m][n] = __builtin_amdgcn_mfma_f32_16x16x32_bf16(Bt[n][k], At[m][k], acc[ai][bj][m][n], 0, 0, 0); __builtin_amdgcn_s_setprio(0); } while (0)
; #define PG8_WAIT_V(n) asm volatile("s_waitcnt vmcnt(" #n ")" ::: "memory")
; #define PG8_WAIT_L(n) asm volatile("s_waitcnt lgkmcnt(" #n ")" ::: "memory")
; #define PG8_BAR __builtin_amdgcn_s_barrier()
; #define PG8_SCHED __builtin_amdgcn_sched_barrier(0)
; template <class Epi, class Sched, bool ALIGN_EPI = false, bool SP2 = false>
; __device__ __forceinline__ void gemm_phase(PG8_LAS unsigned char* lds, const Gemm g, const Sched& S, const Epi& E) {
;     ...
;             PG8_LDB(B0, 1, 0); PG8_LDB(B1, 1, 1); PG8_SCHED; PG8_LDA(At, 1, 0); PG8_STAGE(PG8_SA(0, 1), a2 + hstep, voffA);
;             PG8_WAIT_V(8); PG8_WAIT_L(0); PG8_BAR; PG8_MMA(0, 0, At, B0); PG8_MMA(0, 1, At, B1); PG8_BAR; PG8_SCHED;
;             PG8_LDA(At, 1, 1); PG8_STAGE(PG8_SB(1, 0), b3, voffB); PG8_STAGE(PG8_SB(1, 1), b3 + hstep, voffB); PG8_STAGE(PG8_SA(1, 0), a3, voffA);
;             PG8_WAIT_V(8); PG8_WAIT_L(0); PG8_BAR; PG8_MMA(1, 0, At, B0); PG8_MMA(1, 1, At, B1); PG8_BAR; PG8_SCHED;
	s_add_i32 s81, 0, 0x18000
	v_add_u32_e32 v150, s81, v153
	s_add_i32 s82, 0, 0x1c000
	ds_read_b128 v[130:133], v150
	ds_read_b128 v[134:137], v150 offset:1024
	ds_read_b128 v[138:141], v150 offset:2048
	ds_read_b128 v[170:173], v150 offset:3072
	v_add_u32_e32 v150, s82, v153
	ds_read_b128 v[174:177], v150
	ds_read_b128 v[178:181], v150 offset:1024
	ds_read_b128 v[182:185], v150 offset:2048
	ds_read_b128 v[186:189], v150 offset:3072
	s_add_u32 s14, s14, 0x100000
	s_addc_u32 s15, s15, 0
	s_mov_b32 m0, s89
	ds_read_b128 v[190:193], v230 offset:32768
	ds_read_b128 v[194:197], v230 offset:33792
	ds_read_b128 v[198:201], v230 offset:34816
	ds_read_b128 v[202:205], v230 offset:35840
	ds_read_b128 v[206:209], v230 offset:36864
	ds_read_b128 v[210:213], v230 offset:37888
	ds_read_b128 v[214:217], v230 offset:38912
	ds_read_b128 v[218:221], v230 offset:39936
	global_load_lds_dwordx4 v142, s[14:15]
	s_mov_b32 m0, s90
	s_nop 0
	global_load_lds_dwordx4 v146, s[14:15]
	s_waitcnt vmcnt(8)
	s_waitcnt lgkmcnt(0)
	s_barrier
	v_mfma_f32_16x16x32_bf16 v[126:129], v[130:133], v[190:193], v[126:129]
	v_mfma_f32_16x16x32_bf16 v[126:129], v[134:137], v[194:197], v[126:129]
	v_mfma_f32_16x16x32_bf16 v[122:125], v[138:141], v[190:193], v[122:125]
	v_mfma_f32_16x16x32_bf16 v[122:125], v[170:173], v[194:197], v[122:125]
	v_mfma_f32_16x16x32_bf16 v[110:113], v[130:133], v[198:201], v[110:113]
	v_mfma_f32_16x16x32_bf16 v[110:113], v[134:137], v[202:205], v[110:113]
	v_mfma_f32_16x16x32_bf16 v[106:109], v[138:141], v[198:201], v[106:109]
	v_mfma_f32_16x16x32_bf16 v[106:109], v[170:173], v[202:205], v[106:109]
	v_mfma_f32_16x16x32_bf16 v[94:97], v[130:133], v[206:209], v[94:97]
	v_mfma_f32_16x16x32_bf16 v[94:97], v[134:137], v[210:213], v[94:97]
	v_mfma_f32_16x16x32_bf16 v[90:93], v[138:141], v[206:209], v[90:93]
	v_mfma_f32_16x16x32_bf16 v[90:93], v[170:173], v[210:213], v[90:93]
	v_mfma_f32_16x16x32_bf16 v[78:81], v[130:133], v[214:217], v[78:81]
	v_mfma_f32_16x16x32_bf16 v[78:81], v[134:137], v[218:221], v[78:81]
	v_mfma_f32_16x16x32_bf16 v[74:77], v[138:141], v[214:217], v[74:77]
	v_mfma_f32_16x16x32_bf16 v[74:77], v[170:173], v[218:221], v[74:77]
	v_mfma_f32_16x16x32_bf16 v[118:121], v[174:177], v[190:193], v[118:121]
	v_mfma_f32_16x16x32_bf16 v[118:121], v[178:181], v[194:197], v[118:121]
	v_mfma_f32_16x16x32_bf16 v[114:117], v[182:185], v[190:193], v[114:117]
	v_mfma_f32_16x16x32_bf16 v[114:117], v[186:189], v[194:197], v[114:117]
	v_mfma_f32_16x16x32_bf16 v[102:105], v[174:177], v[198:201], v[102:105]
	v_mfma_f32_16x16x32_bf16 v[102:105], v[178:181], v[202:205], v[102:105]
	v_mfma_f32_16x16x32_bf16 v[98:101], v[182:185], v[198:201], v[98:101]
	v_mfma_f32_16x16x32_bf16 v[98:101], v[186:189], v[202:205], v[98:101]
	v_mfma_f32_16x16x32_bf16 v[86:89], v[174:177], v[206:209], v[86:89]
	v_mfma_f32_16x16x32_bf16 v[86:89], v[178:181], v[210:213], v[86:89]
	v_mfma_f32_16x16x32_bf16 v[82:85], v[182:185], v[206:209], v[82:85]
	v_mfma_f32_16x16x32_bf16 v[82:85], v[186:189], v[210:213], v[82:85]
	v_mfma_f32_16x16x32_bf16 v[70:73], v[174:177], v[214:217], v[70:73]
	v_mfma_f32_16x16x32_bf16 v[70:73], v[178:181], v[218:221], v[70:73]
	v_mfma_f32_16x16x32_bf16 v[66:69], v[182:185], v[214:217], v[66:69]
	v_mfma_f32_16x16x32_bf16 v[66:69], v[186:189], v[218:221], v[66:69]
	s_barrier
	s_add_u32 s100, s14, 0xfff00080
	s_addc_u32 s101, s15, -1
	s_add_u32 s98, s12, 0x80
	s_addc_u32 s99, s13, 0
	s_add_i32 s14, s81, s67
	s_mov_b32 m0, s14
	ds_read_b128 v[190:193], v230 offset:49152
	ds_read_b128 v[194:197], v230 offset:50176
	ds_read_b128 v[198:201], v230 offset:51200
	ds_read_b128 v[202:205], v230 offset:52224
	ds_read_b128 v[206:209], v230 offset:53248
	ds_read_b128 v[210:213], v230 offset:54272
	ds_read_b128 v[214:217], v230 offset:55296
	ds_read_b128 v[218:221], v230 offset:56320
	global_load_lds_dwordx4 v144, s[98:99]
	s_add_i32 m0, s14, 0x2000
	s_add_u32 s12, s12, 0x100080
	s_addc_u32 s13, s13, 0
	s_add_i32 s14, s82, s67
	global_load_lds_dwordx4 v148, s[98:99]
	s_mov_b32 m0, s14
	s_nop 0
	global_load_lds_dwordx4 v144, s[12:13]
	s_add_i32 m0, s14, 0x2000
	s_nop 0
	global_load_lds_dwordx4 v148, s[12:13]
	s_mov_b32 m0, s93
	s_nop 0
	global_load_lds_dwordx4 v142, s[100:101]
	s_mov_b32 m0, s62
	s_nop 0
	global_load_lds_dwordx4 v146, s[100:101]
	s_waitcnt vmcnt(8)
	s_waitcnt lgkmcnt(0)
	s_barrier
	v_mfma_f32_16x16x32_bf16 v[62:65], v[130:133], v[190:193], v[62:65]
	v_mfma_f32_16x16x32_bf16 v[62:65], v[134:137], v[194:197], v[62:65]
	v_mfma_f32_16x16x32_bf16 v[58:61], v[138:141], v[190:193], v[58:61]
	v_mfma_f32_16x16x32_bf16 v[58:61], v[170:173], v[194:197], v[58:61]
	v_mfma_f32_16x16x32_bf16 v[46:49], v[130:133], v[198:201], v[46:49]
	v_mfma_f32_16x16x32_bf16 v[46:49], v[134:137], v[202:205], v[46:49]
	v_mfma_f32_16x16x32_bf16 v[42:45], v[138:141], v[198:201], v[42:45]
	v_mfma_f32_16x16x32_bf16 v[42:45], v[170:173], v[202:205], v[42:45]
	v_mfma_f32_16x16x32_bf16 v[30:33], v[130:133], v[206:209], v[30:33]
	v_mfma_f32_16x16x32_bf16 v[30:33], v[134:137], v[210:213], v[30:33]
	v_mfma_f32_16x16x32_bf16 v[26:29], v[138:141], v[206:209], v[26:29]
	v_mfma_f32_16x16x32_bf16 v[26:29], v[170:173], v[210:213], v[26:29]
	v_mfma_f32_16x16x32_bf16 v[14:17], v[130:133], v[214:217], v[14:17]
	v_mfma_f32_16x16x32_bf16 v[14:17], v[134:137], v[218:221], v[14:17]
	v_mfma_f32_16x16x32_bf16 v[10:13], v[138:141], v[214:217], v[10:13]
	v_mfma_f32_16x16x32_bf16 v[10:13], v[170:173], v[218:221], v[10:13]
	v_mfma_f32_16x16x32_bf16 v[54:57], v[174:177], v[190:193], v[54:57]
	v_mfma_f32_16x16x32_bf16 v[54:57], v[178:181], v[194:197], v[54:57]
	v_mfma_f32_16x16x32_bf16 v[50:53], v[182:185], v[190:193], v[50:53]
	v_mfma_f32_16x16x32_bf16 v[50:53], v[186:189], v[194:197], v[50:53]
	v_mfma_f32_16x16x32_bf16 v[38:41], v[174:177], v[198:201], v[38:41]
	v_mfma_f32_16x16x32_bf16 v[38:41], v[178:181], v[202:205], v[38:41]
	v_mfma_f32_16x16x32_bf16 v[34:37], v[182:185], v[198:201], v[34:37]
	v_mfma_f32_16x16x32_bf16 v[34:37], v[186:189], v[202:205], v[34:37]
	v_mfma_f32_16x16x32_bf16 v[22:25], v[174:177], v[206:209], v[22:25]
	v_mfma_f32_16x16x32_bf16 v[22:25], v[178:181], v[210:213], v[22:25]
	v_mfma_f32_16x16x32_bf16 v[18:21], v[182:185], v[206:209], v[18:21]
	v_mfma_f32_16x16x32_bf16 v[18:21], v[186:189], v[210:213], v[18:21]
	v_mfma_f32_16x16x32_bf16 v[6:9], v[174:177], v[214:217], v[6:9]
	v_mfma_f32_16x16x32_bf16 v[6:9], v[178:181], v[218:221], v[6:9]
	v_mfma_f32_16x16x32_bf16 v[2:5], v[182:185], v[214:217], v[2:5]
	v_mfma_f32_16x16x32_bf16 v[2:5], v[186:189], v[218:221], v[2:5]
	s_barrier
	s_add_i32 s80, s80, 2
	s_add_u32 s10, s10, 0x100
	s_addc_u32 s11, s11, 0
	s_add_u32 s71, s71, 0x100
	s_addc_u32 s77, s77, 0
	s_cmp_gt_u32 s80, 61
	s_cbranch_scc0 .LBB0_366
	s_and_b64 vcc, exec, s[28:29]
	s_cbranch_vccz .LBB0_369
	s_barrier

; #define PG8_STAGE(bufoff, gbase, voff) do { _Pragma("unroll") for (int _i = 0; _i < 2; ++_i) \
;         __builtin_amdgcn_global_load_lds((const unsigned*)((const char*)(gbase) + (voff)[_i]), (PG8_LAS unsigned*)(lds + (bufoff) + ldsw + _i * 8192), 16, 0, 0); } while (0)
; #define PG8_LDA(dst, b, h) do { _Pragma("unroll") for (int m = 0; m < 4; ++m) _Pragma("unroll") for (int k = 0; k < 2; ++k) dst[m][k] = *(const PG8_LAS bf16x8*)(lds + PG8_SA(b, h) + aoff + m * 2048 + k * 1024); } while (0)
; #define PG8_LDB(dst, b, h) do { _Pragma("unroll") for (int n = 0; n < 2; ++n) _Pragma("unroll") for (int k = 0; k < 2; ++k) dst[n][k] = *(const PG8_LAS bf16x8*)(lds + PG8_SB(b, h) + boff + n * 2048 + k * 1024); } while (0)
; #define PG8_MMA(ai, bj, At, Bt) do { __builtin_amdgcn_s_setprio(1); _Pragma("unroll") for (int m = 0; m < 4; ++m) _Pragma("unroll") for (int n = 0; n < 2; ++n) _Pragma("unroll") for (int k = 0; k < 2; ++k) \
;         acc[ai][bj][m][n] = __builtin_amdgcn_mfma_f32_16x16x32_bf16(Bt[n][k], At[m][k], acc[ai][bj][m][n], 0, 0, 0); __builtin_amdgcn_s_setprio(0); } while (0)
; #define PG8_WAIT_V(n) asm volatile("s_waitcnt vmcnt(" #n ")" ::: "memory")
; #define PG8_WAIT_L(n) asm volatile("s_waitcnt lgkmcnt(" #n ")" ::: "memory")
; #define PG8_BAR __builtin_amdgcn_s_barrier()
; #define PG8_SCHED __builtin_amdgcn_sched_barrier(0)
; template <class Epi, class Sched, bool ALIGN_EPI = false, bool SP2 = false>
; __device__ __forceinline__ void gemm_phase(PG8_LAS unsigned char* lds, const Gemm g, const Sched& S, const Epi& E) {
;     ...
;             PG8_LDB(B0, 0, 0); PG8_LDB(B1, 0, 1); PG8_SCHED; PG8_LDA(At, 0, 0); PG8_STAGE(PG8_SA(1, 1), a1 + hstep, voffA);
;             PG8_WAIT_V(8); PG8_WAIT_L(0); PG8_BAR; PG8_MMA(0, 0, At, B0); PG8_MMA(0, 1, At, B1); PG8_BAR; PG8_SCHED;
;             PG8_LDA(At, 0, 1); PG8_STAGE(PG8_SB(0, 0), b2, voffB); PG8_STAGE(PG8_SB(0, 1), b2 + hstep, voffB); PG8_STAGE(PG8_SA(0, 0), a2, voffA);
;             PG8_WAIT_V(8); PG8_WAIT_L(0); PG8_BAR; PG8_MMA(1, 0, At, B0); PG8_MMA(1, 1, At, B1); PG8_BAR; PG8_SCHED;
.LBB0_2487:
	v_add_u32_e32 v3, s67, v183
	s_add_i32 s81, s50, 2
	ds_read_b128 v[154:157], v3
	ds_read_b128 v[158:161], v3 offset:1024
	ds_read_b128 v[162:165], v3 offset:2048
	ds_read_b128 v[166:169], v3 offset:3072
	v_add_u32_e32 v3, s68, v183
	s_add_u32 s51, s42, s46
	ds_read_b128 v[170:173], v3
	ds_read_b128 v[174:177], v3 offset:1024
	ds_read_b128 v[178:181], v3 offset:2048
	ds_read_b128 v[184:187], v3 offset:3072
	s_addc_u32 s52, s43, s47
	s_add_u32 s51, s51, 0x100
	s_addc_u32 s52, s52, 0
	s_add_u32 s82, s79, s46
	s_addc_u32 s83, s80, s47
	s_cmp_eq_u32 s9, s50
	s_cselect_b32 s53, s27, s52
	s_cselect_b32 s52, s35, s51
	s_cselect_b32 s51, s31, s83
	s_cselect_b32 s50, s78, s82
	v_lshl_add_u64 v[4:5], v[150:151], 0, s[46:47]
	s_add_i32 m0, s11, 0xc000
	ds_read_b128 v[188:191], v211
	ds_read_b128 v[192:195], v211 offset:1024
	ds_read_b128 v[196:199], v211 offset:2048
	ds_read_b128 v[200:203], v211 offset:3072
	ds_read_b128 v[204:207], v211 offset:4096
	ds_read_b128 v[212:215], v211 offset:5120
	ds_read_b128 v[216:219], v211 offset:6144
	ds_read_b128 v[220:223], v211 offset:7168
	global_load_lds_dwordx4 v[4:5], off
	v_lshl_add_u64 v[4:5], v[152:153], 0, s[46:47]
	s_add_i32 m0, s11, 0xe000
	s_nop 0
	global_load_lds_dwordx4 v[4:5], off
	s_waitcnt vmcnt(8)
	s_waitcnt lgkmcnt(0)
	s_barrier
	v_mfma_f32_16x16x32_bf16 v[130:133], v[154:157], v[188:191], v[130:133]
	v_mfma_f32_16x16x32_bf16 v[130:133], v[158:161], v[192:195], v[130:133]
	v_mfma_f32_16x16x32_bf16 v[126:129], v[162:165], v[188:191], v[126:129]
	v_mfma_f32_16x16x32_bf16 v[126:129], v[166:169], v[192:195], v[126:129]
	v_mfma_f32_16x16x32_bf16 v[114:117], v[154:157], v[196:199], v[114:117]
	v_mfma_f32_16x16x32_bf16 v[114:117], v[158:161], v[200:203], v[114:117]
	v_mfma_f32_16x16x32_bf16 v[110:113], v[162:165], v[196:199], v[110:113]
	v_mfma_f32_16x16x32_bf16 v[110:113], v[166:169], v[200:203], v[110:113]
	v_mfma_f32_16x16x32_bf16 v[98:101], v[154:157], v[204:207], v[98:101]
	v_mfma_f32_16x16x32_bf16 v[98:101], v[158:161], v[212:215], v[98:101]
	v_mfma_f32_16x16x32_bf16 v[94:97], v[162:165], v[204:207], v[94:97]
	v_mfma_f32_16x16x32_bf16 v[94:97], v[166:169], v[212:215], v[94:97]
	v_mfma_f32_16x16x32_bf16 v[82:85], v[154:157], v[216:219], v[82:85]
	v_mfma_f32_16x16x32_bf16 v[82:85], v[158:161], v[220:223], v[82:85]
	v_mfma_f32_16x16x32_bf16 v[78:81], v[162:165], v[216:219], v[78:81]
	v_mfma_f32_16x16x32_bf16 v[78:81], v[166:169], v[220:223], v[78:81]
	v_mfma_f32_16x16x32_bf16 v[122:125], v[170:173], v[188:191], v[122:125]
	v_mfma_f32_16x16x32_bf16 v[122:125], v[174:177], v[192:195], v[122:125]
	v_mfma_f32_16x16x32_bf16 v[118:121], v[178:181], v[188:191], v[118:121]
	v_mfma_f32_16x16x32_bf16 v[118:121], v[184:187], v[192:195], v[118:121]
	v_mfma_f32_16x16x32_bf16 v[106:109], v[170:173], v[196:199], v[106:109]
	v_mfma_f32_16x16x32_bf16 v[106:109], v[174:177], v[200:203], v[106:109]
	v_mfma_f32_16x16x32_bf16 v[102:105], v[178:181], v[196:199], v[102:105]
	v_mfma_f32_16x16x32_bf16 v[102:105], v[184:187], v[200:203], v[102:105]
	v_mfma_f32_16x16x32_bf16 v[90:93], v[170:173], v[204:207], v[90:93]
	v_mfma_f32_16x16x32_bf16 v[90:93], v[174:177], v[212:215], v[90:93]
	v_mfma_f32_16x16x32_bf16 v[86:89], v[178:181], v[204:207], v[86:89]
	v_mfma_f32_16x16x32_bf16 v[86:89], v[184:187], v[212:215], v[86:89]
	v_mfma_f32_16x16x32_bf16 v[74:77], v[170:173], v[216:219], v[74:77]
	v_mfma_f32_16x16x32_bf16 v[74:77], v[174:177], v[220:223], v[74:77]
	v_mfma_f32_16x16x32_bf16 v[70:73], v[178:181], v[216:219], v[70:73]
	v_mfma_f32_16x16x32_bf16 v[70:73], v[184:187], v[220:223], v[70:73]
	s_barrier
	s_add_i32 s82, s67, s55
	s_mov_b32 m0, s82
	ds_read_b128 v[188:191], v211 offset:16384
	ds_read_b128 v[192:195], v211 offset:17408
	ds_read_b128 v[196:199], v211 offset:18432
	ds_read_b128 v[200:203], v211 offset:19456
	ds_read_b128 v[204:207], v211 offset:20480
	ds_read_b128 v[212:215], v211 offset:21504
	ds_read_b128 v[216:219], v211 offset:22528
	ds_read_b128 v[220:223], v211 offset:23552
	global_load_lds_dwordx4 v134, s[50:51]
	s_add_i32 m0, s82, 0x2000
	s_add_u32 s82, s50, 0x100000
	s_addc_u32 s83, s51, 0
	s_add_i32 s84, s68, s55
	global_load_lds_dwordx4 v136, s[50:51]
	s_mov_b32 m0, s84
	s_nop 0
	global_load_lds_dwordx4 v134, s[82:83]
	s_add_i32 m0, s84, 0x2000
	s_nop 0
	global_load_lds_dwordx4 v136, s[82:83]
	s_mov_b32 m0, s11
	s_nop 0
	global_load_lds_dwordx4 v134, s[52:53]
	s_mov_b32 m0, s57
	s_nop 0
	global_load_lds_dwordx4 v136, s[52:53]
	s_waitcnt vmcnt(8)
	s_waitcnt lgkmcnt(0)
	s_barrier
	v_mfma_f32_16x16x32_bf16 v[66:69], v[154:157], v[188:191], v[66:69]
	v_mfma_f32_16x16x32_bf16 v[66:69], v[158:161], v[192:195], v[66:69]
	v_mfma_f32_16x16x32_bf16 v[62:65], v[162:165], v[188:191], v[62:65]
	v_mfma_f32_16x16x32_bf16 v[62:65], v[166:169], v[192:195], v[62:65]
	v_mfma_f32_16x16x32_bf16 v[50:53], v[154:157], v[196:199], v[50:53]
	v_mfma_f32_16x16x32_bf16 v[50:53], v[158:161], v[200:203], v[50:53]
	v_mfma_f32_16x16x32_bf16 v[46:49], v[162:165], v[196:199], v[46:49]
	v_mfma_f32_16x16x32_bf16 v[46:49], v[166:169], v[200:203], v[46:49]
	v_mfma_f32_16x16x32_bf16 v[34:37], v[154:157], v[204:207], v[34:37]
	v_mfma_f32_16x16x32_bf16 v[34:37], v[158:161], v[212:215], v[34:37]
	v_mfma_f32_16x16x32_bf16 v[30:33], v[162:165], v[204:207], v[30:33]
	v_mfma_f32_16x16x32_bf16 v[30:33], v[166:169], v[212:215], v[30:33]
	v_mfma_f32_16x16x32_bf16 v[18:21], v[154:157], v[216:219], v[18:21]
	v_mfma_f32_16x16x32_bf16 v[18:21], v[158:161], v[220:223], v[18:21]
	v_mfma_f32_16x16x32_bf16 v[14:17], v[162:165], v[216:219], v[14:17]
	v_mfma_f32_16x16x32_bf16 v[14:17], v[166:169], v[220:223], v[14:17]
	v_mfma_f32_16x16x32_bf16 v[58:61], v[170:173], v[188:191], v[58:61]
	v_mfma_f32_16x16x32_bf16 v[58:61], v[174:177], v[192:195], v[58:61]
	v_mfma_f32_16x16x32_bf16 v[54:57], v[178:181], v[188:191], v[54:57]
	v_mfma_f32_16x16x32_bf16 v[54:57], v[184:187], v[192:195], v[54:57]
	v_mfma_f32_16x16x32_bf16 v[42:45], v[170:173], v[196:199], v[42:45]
	v_mfma_f32_16x16x32_bf16 v[42:45], v[174:177], v[200:203], v[42:45]
	v_mfma_f32_16x16x32_bf16 v[38:41], v[178:181], v[196:199], v[38:41]
	v_mfma_f32_16x16x32_bf16 v[38:41], v[184:187], v[200:203], v[38:41]
	v_mfma_f32_16x16x32_bf16 v[26:29], v[170:173], v[204:207], v[26:29]
	v_mfma_f32_16x16x32_bf16 v[26:29], v[174:177], v[212:215], v[26:29]
	v_mfma_f32_16x16x32_bf16 v[22:25], v[178:181], v[204:207], v[22:25]
	v_mfma_f32_16x16x32_bf16 v[22:25], v[184:187], v[212:215], v[22:25]
	v_mfma_f32_16x16x32_bf16 v[10:13], v[170:173], v[216:219], v[10:13]
	v_mfma_f32_16x16x32_bf16 v[10:13], v[174:177], v[220:223], v[10:13]
	v_mfma_f32_16x16x32_bf16 v[4:7], v[178:181], v[216:219], v[6:9]
	v_mfma_f32_16x16x32_bf16 v[4:7], v[184:187], v[220:223], v[4:7]
	s_barrier
; #define PG8_STAGE(bufoff, gbase, voff) do { _Pragma("unroll") for (int _i = 0; _i < 2; ++_i) \
;         __builtin_amdgcn_global_load_lds((const unsigned*)((const char*)(gbase) + (voff)[_i]), (PG8_LAS unsigned*)(lds + (bufoff) + ldsw + _i * 8192), 16, 0, 0); } while (0)
; #define PG8_LDA(dst, b, h) do { _Pragma("unroll") for (int m = 0; m < 4; ++m) _Pragma("unroll") for (int k = 0; k < 2; ++k) dst[m][k] = *(const PG8_LAS bf16x8*)(lds + PG8_SA(b, h) + aoff + m * 2048 + k * 1024); } while (0)
; #define PG8_LDB(dst, b, h) do { _Pragma("unroll") for (int n = 0; n < 2; ++n) _Pragma("unroll") for (int k = 0; k < 2; ++k) dst[n][k] = *(const PG8_LAS bf16x8*)(lds + PG8_SB(b, h) + boff + n * 2048 + k * 1024); } while (0)
; #define PG8_MMA(ai, bj, At, Bt) do { __builtin_amdgcn_s_setprio(1); _Pragma("unroll") for (int m = 0; m < 4; ++m) _Pragma("unroll") for (int n = 0; n < 2; ++n) _Pragma("unroll") for (int k = 0; k < 2; ++k) \
;         acc[ai][bj][m][n] = __builtin_amdgcn_mfma_f32_16x16x32_bf16(Bt[n][k], At[m][k], acc[ai][bj][m][n], 0, 0, 0); __builtin_amdgcn_s_setprio(0); } while (0)
; #define PG8_WAIT_V(n) asm volatile("s_waitcnt vmcnt(" #n ")" ::: "memory")
; #define PG8_WAIT_L(n) asm volatile("s_waitcnt lgkmcnt(" #n ")" ::: "memory")
; #define PG8_BAR __builtin_amdgcn_s_barrier()
; #define PG8_SCHED __builtin_amdgcn_sched_barrier(0)
; template <class Epi, class Sched, bool ALIGN_EPI = false, bool SP2 = false>
; __device__ __forceinline__ void gemm_phase(PG8_LAS unsigned char* lds, const Gemm g, const Sched& S, const Epi& E) {
;     ...
;             PG8_LDB(B0, 1, 0); PG8_LDB(B1, 1, 1); PG8_SCHED; PG8_LDA(At, 1, 0); PG8_STAGE(PG8_SA(0, 1), a2 + hstep, voffA);
;             PG8_WAIT_V(8); PG8_WAIT_L(0); PG8_BAR; PG8_MMA(0, 0, At, B0); PG8_MMA(0, 1, At, B1); PG8_BAR; PG8_SCHED;
;             PG8_LDA(At, 1, 1); PG8_STAGE(PG8_SB(1, 0), b3, voffB); PG8_STAGE(PG8_SB(1, 1), b3 + hstep, voffB); PG8_STAGE(PG8_SA(1, 0), a3, voffA);
;             PG8_WAIT_V(8); PG8_WAIT_L(0); PG8_BAR; PG8_MMA(1, 0, At, B0); PG8_MMA(1, 1, At, B1); PG8_BAR; PG8_SCHED;
	s_add_i32 s82, 0, 0x18000
	v_add_u32_e32 v3, s82, v183
	s_add_i32 s83, 0, 0x1c000
	ds_read_b128 v[154:157], v3
	ds_read_b128 v[158:161], v3 offset:1024
	ds_read_b128 v[162:165], v3 offset:2048
	ds_read_b128 v[166:169], v3 offset:3072
	v_add_u32_e32 v3, s83, v183
	ds_read_b128 v[170:173], v3
	ds_read_b128 v[174:177], v3 offset:1024
	ds_read_b128 v[178:181], v3 offset:2048
	ds_read_b128 v[184:187], v3 offset:3072
	s_add_u32 s52, s52, 0x100000
	s_addc_u32 s53, s53, 0
	s_mov_b32 m0, s60
	ds_read_b128 v[188:191], v211 offset:32768
	ds_read_b128 v[192:195], v211 offset:33792
	ds_read_b128 v[196:199], v211 offset:34816
	ds_read_b128 v[200:203], v211 offset:35840
	ds_read_b128 v[204:207], v211 offset:36864
	ds_read_b128 v[212:215], v211 offset:37888
	ds_read_b128 v[216:219], v211 offset:38912
	ds_read_b128 v[220:223], v211 offset:39936
	global_load_lds_dwordx4 v134, s[52:53]
	s_mov_b32 m0, s61
	s_nop 0
	global_load_lds_dwordx4 v136, s[52:53]
	s_waitcnt vmcnt(8)
	s_waitcnt lgkmcnt(0)
	s_barrier
	v_mfma_f32_16x16x32_bf16 v[130:133], v[154:157], v[188:191], v[130:133]
	v_mfma_f32_16x16x32_bf16 v[130:133], v[158:161], v[192:195], v[130:133]
	v_mfma_f32_16x16x32_bf16 v[126:129], v[162:165], v[188:191], v[126:129]
	v_mfma_f32_16x16x32_bf16 v[126:129], v[166:169], v[192:195], v[126:129]
	v_mfma_f32_16x16x32_bf16 v[114:117], v[154:157], v[196:199], v[114:117]
	v_mfma_f32_16x16x32_bf16 v[114:117], v[158:161], v[200:203], v[114:117]
	v_mfma_f32_16x16x32_bf16 v[110:113], v[162:165], v[196:199], v[110:113]
	v_mfma_f32_16x16x32_bf16 v[110:113], v[166:169], v[200:203], v[110:113]
	v_mfma_f32_16x16x32_bf16 v[98:101], v[154:157], v[204:207], v[98:101]
	v_mfma_f32_16x16x32_bf16 v[98:101], v[158:161], v[212:215], v[98:101]
	v_mfma_f32_16x16x32_bf16 v[94:97], v[162:165], v[204:207], v[94:97]
	v_mfma_f32_16x16x32_bf16 v[94:97], v[166:169], v[212:215], v[94:97]
	v_mfma_f32_16x16x32_bf16 v[82:85], v[154:157], v[216:219], v[82:85]
	v_mfma_f32_16x16x32_bf16 v[82:85], v[158:161], v[220:223], v[82:85]
	v_mfma_f32_16x16x32_bf16 v[78:81], v[162:165], v[216:219], v[78:81]
	v_mfma_f32_16x16x32_bf16 v[78:81], v[166:169], v[220:223], v[78:81]
	v_mfma_f32_16x16x32_bf16 v[122:125], v[170:173], v[188:191], v[122:125]
	v_mfma_f32_16x16x32_bf16 v[122:125], v[174:177], v[192:195], v[122:125]
	v_mfma_f32_16x16x32_bf16 v[118:121], v[178:181], v[188:191], v[118:121]
	v_mfma_f32_16x16x32_bf16 v[118:121], v[184:187], v[192:195], v[118:121]
	v_mfma_f32_16x16x32_bf16 v[106:109], v[170:173], v[196:199], v[106:109]
	v_mfma_f32_16x16x32_bf16 v[106:109], v[174:177], v[200:203], v[106:109]
	v_mfma_f32_16x16x32_bf16 v[102:105], v[178:181], v[196:199], v[102:105]
	v_mfma_f32_16x16x32_bf16 v[102:105], v[184:187], v[200:203], v[102:105]
	v_mfma_f32_16x16x32_bf16 v[90:93], v[170:173], v[204:207], v[90:93]
	v_mfma_f32_16x16x32_bf16 v[90:93], v[174:177], v[212:215], v[90:93]
	v_mfma_f32_16x16x32_bf16 v[86:89], v[178:181], v[204:207], v[86:89]
	v_mfma_f32_16x16x32_bf16 v[86:89], v[184:187], v[212:215], v[86:89]
	v_mfma_f32_16x16x32_bf16 v[74:77], v[170:173], v[216:219], v[74:77]
	v_mfma_f32_16x16x32_bf16 v[74:77], v[174:177], v[220:223], v[74:77]
	v_mfma_f32_16x16x32_bf16 v[70:73], v[178:181], v[216:219], v[70:73]
	v_mfma_f32_16x16x32_bf16 v[70:73], v[184:187], v[220:223], v[70:73]
	s_barrier
	s_add_u32 s100, s52, 0xfff00080
	s_addc_u32 s101, s53, -1
	s_add_u32 s98, s50, 0x80
	s_addc_u32 s99, s51, 0
	s_add_i32 s52, s82, s55
	s_mov_b32 m0, s52
	ds_read_b128 v[188:191], v211 offset:49152
	ds_read_b128 v[192:195], v211 offset:50176
	ds_read_b128 v[196:199], v211 offset:51200
	ds_read_b128 v[200:203], v211 offset:52224
	ds_read_b128 v[204:207], v211 offset:53248
	ds_read_b128 v[212:215], v211 offset:54272
	ds_read_b128 v[216:219], v211 offset:55296
	ds_read_b128 v[220:223], v211 offset:56320
	global_load_lds_dwordx4 v134, s[98:99]
	s_add_i32 m0, s52, 0x2000
	s_add_u32 s50, s50, 0x100080
	s_addc_u32 s51, s51, 0
	s_add_i32 s52, s83, s55
	global_load_lds_dwordx4 v136, s[98:99]
	s_mov_b32 m0, s52
	s_nop 0
	global_load_lds_dwordx4 v134, s[50:51]
	s_add_i32 m0, s52, 0x2000
	s_nop 0
	global_load_lds_dwordx4 v136, s[50:51]
	s_mov_b32 m0, s63
	s_nop 0
	global_load_lds_dwordx4 v134, s[100:101]
	s_mov_b32 m0, s64
	s_nop 0
	global_load_lds_dwordx4 v136, s[100:101]
	s_waitcnt vmcnt(8)
	s_waitcnt lgkmcnt(0)
	s_barrier
	v_mfma_f32_16x16x32_bf16 v[66:69], v[154:157], v[188:191], v[66:69]
	v_mfma_f32_16x16x32_bf16 v[66:69], v[158:161], v[192:195], v[66:69]
	v_mfma_f32_16x16x32_bf16 v[62:65], v[162:165], v[188:191], v[62:65]
	v_mfma_f32_16x16x32_bf16 v[62:65], v[166:169], v[192:195], v[62:65]
	v_mfma_f32_16x16x32_bf16 v[50:53], v[154:157], v[196:199], v[50:53]
	v_mfma_f32_16x16x32_bf16 v[50:53], v[158:161], v[200:203], v[50:53]
	v_mfma_f32_16x16x32_bf16 v[46:49], v[162:165], v[196:199], v[46:49]
	v_mfma_f32_16x16x32_bf16 v[46:49], v[166:169], v[200:203], v[46:49]
	v_mfma_f32_16x16x32_bf16 v[34:37], v[154:157], v[204:207], v[34:37]
	v_mfma_f32_16x16x32_bf16 v[34:37], v[158:161], v[212:215], v[34:37]
	v_mfma_f32_16x16x32_bf16 v[30:33], v[162:165], v[204:207], v[30:33]
	v_mfma_f32_16x16x32_bf16 v[30:33], v[166:169], v[212:215], v[30:33]
	v_mfma_f32_16x16x32_bf16 v[18:21], v[154:157], v[216:219], v[18:21]
	v_mfma_f32_16x16x32_bf16 v[18:21], v[158:161], v[220:223], v[18:21]
	v_mfma_f32_16x16x32_bf16 v[14:17], v[162:165], v[216:219], v[14:17]
	v_mfma_f32_16x16x32_bf16 v[14:17], v[166:169], v[220:223], v[14:17]
	v_mfma_f32_16x16x32_bf16 v[58:61], v[170:173], v[188:191], v[58:61]
	v_mfma_f32_16x16x32_bf16 v[58:61], v[174:177], v[192:195], v[58:61]
	v_mfma_f32_16x16x32_bf16 v[54:57], v[178:181], v[188:191], v[54:57]
	v_mfma_f32_16x16x32_bf16 v[54:57], v[184:187], v[192:195], v[54:57]
	v_mfma_f32_16x16x32_bf16 v[42:45], v[170:173], v[196:199], v[42:45]
	v_mfma_f32_16x16x32_bf16 v[42:45], v[174:177], v[200:203], v[42:45]
	v_mfma_f32_16x16x32_bf16 v[38:41], v[178:181], v[196:199], v[38:41]
	v_mfma_f32_16x16x32_bf16 v[38:41], v[184:187], v[200:203], v[38:41]
	v_mfma_f32_16x16x32_bf16 v[26:29], v[170:173], v[204:207], v[26:29]
	v_mfma_f32_16x16x32_bf16 v[26:29], v[174:177], v[212:215], v[26:29]
	v_mfma_f32_16x16x32_bf16 v[22:25], v[178:181], v[204:207], v[22:25]
	v_mfma_f32_16x16x32_bf16 v[22:25], v[184:187], v[212:215], v[22:25]
	v_mfma_f32_16x16x32_bf16 v[8:11], v[170:173], v[216:219], v[10:13]
	v_mfma_f32_16x16x32_bf16 v[10:13], v[174:177], v[220:223], v[8:11]
	v_mfma_f32_16x16x32_bf16 v[4:7], v[178:181], v[216:219], v[4:7]
	v_mfma_f32_16x16x32_bf16 v[6:9], v[184:187], v[220:223], v[4:7]
	s_barrier
	s_add_u32 s46, s46, 0x100
	s_addc_u32 s47, s47, 0
	s_cmp_ge_i32 s81, s77
	s_cbranch_scc1 .LBB0_2489
	s_mov_b32 s50, s81
	s_branch .LBB0_2485

; #define PG8_STAGE(bufoff, gbase, voff) do { _Pragma("unroll") for (int _i = 0; _i < 2; ++_i) \
;         __builtin_amdgcn_global_load_lds((const unsigned*)((const char*)(gbase) + (voff)[_i]), (PG8_LAS unsigned*)(lds + (bufoff) + ldsw + _i * 8192), 16, 0, 0); } while (0)
; #define PG8_LDA(dst, b, h) do { _Pragma("unroll") for (int m = 0; m < 4; ++m) _Pragma("unroll") for (int k = 0; k < 2; ++k) dst[m][k] = *(const PG8_LAS bf16x8*)(lds + PG8_SA(b, h) + aoff + m * 2048 + k * 1024); } while (0)
; #define PG8_LDB(dst, b, h) do { _Pragma("unroll") for (int n = 0; n < 2; ++n) _Pragma("unroll") for (int k = 0; k < 2; ++k) dst[n][k] = *(const PG8_LAS bf16x8*)(lds + PG8_SB(b, h) + boff + n * 2048 + k * 1024); } while (0)
; #define PG8_MMA(ai, bj, At, Bt) do { __builtin_amdgcn_s_setprio(1); _Pragma("unroll") for (int m = 0; m < 4; ++m) _Pragma("unroll") for (int n = 0; n < 2; ++n) _Pragma("unroll") for (int k = 0; k < 2; ++k) \
;         acc[ai][bj][m][n] = __builtin_amdgcn_mfma_f32_16x16x32_bf16(Bt[n][k], At[m][k], acc[ai][bj][m][n], 0, 0, 0); __builtin_amdgcn_s_setprio(0); } while (0)
; #define PG8_WAIT_V(n) asm volatile("s_waitcnt vmcnt(" #n ")" ::: "memory")
; #define PG8_WAIT_L(n) asm volatile("s_waitcnt lgkmcnt(" #n ")" ::: "memory")
; #define PG8_BAR __builtin_amdgcn_s_barrier()
; #define PG8_SCHED __builtin_amdgcn_sched_barrier(0)
; template <class Epi, class Sched, bool ALIGN_EPI = false, bool SP2 = false>
; __device__ __forceinline__ void gemm_phase(PG8_LAS unsigned char* lds, const Gemm g, const Sched& S, const Epi& E) {
;     ...
;             PG8_LDB(B0, 0, 0); PG8_LDB(B1, 0, 1); PG8_SCHED; PG8_LDA(At, 0, 0); PG8_STAGE(PG8_SA(1, 1), a1 + hstep, voffA);
;             PG8_WAIT_V(8); PG8_WAIT_L(0); PG8_BAR; PG8_MMA(0, 0, At, B0); PG8_MMA(0, 1, At, B1); PG8_BAR; PG8_SCHED;
;             PG8_LDA(At, 0, 1); PG8_STAGE(PG8_SB(0, 0), b2, voffB); PG8_STAGE(PG8_SB(0, 1), b2 + hstep, voffB); PG8_STAGE(PG8_SA(0, 0), a2, voffA);
;             PG8_WAIT_V(8); PG8_WAIT_L(0); PG8_BAR; PG8_MMA(1, 0, At, B0); PG8_MMA(1, 1, At, B1); PG8_BAR; PG8_SCHED;
.LBB0_2650:
	ds_read_b128 v[10:13], v195
	ds_read_b128 v[14:17], v195 offset:1024
	ds_read_b128 v[42:45], v195 offset:2048
	ds_read_b128 v[46:49], v195 offset:3072
	ds_read_b128 v[50:53], v238
	ds_read_b128 v[54:57], v238 offset:1024
	ds_read_b128 v[58:61], v238 offset:2048
	ds_read_b128 v[62:65], v238 offset:3072
	s_add_u32 s88, s86, 0xfff00080
	s_addc_u32 s89, s87, -1
	s_cmp_eq_u32 s93, 60
	s_cselect_b32 s91, s19, s89
	s_cselect_b32 s90, s69, s88
	s_cselect_b32 s89, s77, s92
	s_cselect_b32 s88, s79, s85
	s_add_i32 m0, s62, 0xc000
	ds_read_b128 v[66:69], v239
	ds_read_b128 v[70:73], v239 offset:1024
	ds_read_b128 v[170:173], v239 offset:2048
	ds_read_b128 v[174:177], v239 offset:3072
	ds_read_b128 v[178:181], v239 offset:4096
	ds_read_b128 v[208:211], v239 offset:5120
	ds_read_b128 v[212:215], v239 offset:6144
	ds_read_b128 v[216:219], v239 offset:7168
	global_load_lds_dwordx4 v200, s[86:87]
	s_add_i32 m0, s62, 0xe000
	s_nop 0
	global_load_lds_dwordx4 v202, s[86:87]
	s_waitcnt vmcnt(8)
	s_waitcnt lgkmcnt(0)
	s_barrier
	v_mfma_f32_16x16x32_bf16 v[6:9], v[10:13], v[66:69], v[6:9]
	v_mfma_f32_16x16x32_bf16 v[6:9], v[14:17], v[70:73], v[6:9]
	v_mfma_f32_16x16x32_bf16 v[2:5], v[42:45], v[66:69], v[2:5]
	v_mfma_f32_16x16x32_bf16 v[2:5], v[46:49], v[70:73], v[2:5]
	v_mfma_f32_16x16x32_bf16 v[158:161], v[10:13], v[170:173], v[158:161]
	v_mfma_f32_16x16x32_bf16 v[158:161], v[14:17], v[174:177], v[158:161]
	v_mfma_f32_16x16x32_bf16 v[154:157], v[42:45], v[170:173], v[154:157]
	v_mfma_f32_16x16x32_bf16 v[154:157], v[46:49], v[174:177], v[154:157]
	v_mfma_f32_16x16x32_bf16 v[142:145], v[10:13], v[178:181], v[142:145]
	v_mfma_f32_16x16x32_bf16 v[142:145], v[14:17], v[208:211], v[142:145]
	v_mfma_f32_16x16x32_bf16 v[138:141], v[42:45], v[178:181], v[138:141]
	v_mfma_f32_16x16x32_bf16 v[138:141], v[46:49], v[208:211], v[138:141]
	v_mfma_f32_16x16x32_bf16 v[126:129], v[10:13], v[212:215], v[126:129]
	v_mfma_f32_16x16x32_bf16 v[126:129], v[14:17], v[216:219], v[126:129]
	v_mfma_f32_16x16x32_bf16 v[122:125], v[42:45], v[212:215], v[122:125]
	v_mfma_f32_16x16x32_bf16 v[122:125], v[46:49], v[216:219], v[122:125]
	v_mfma_f32_16x16x32_bf16 v[166:169], v[50:53], v[66:69], v[166:169]
	v_mfma_f32_16x16x32_bf16 v[166:169], v[54:57], v[70:73], v[166:169]
	v_mfma_f32_16x16x32_bf16 v[66:69], v[58:61], v[66:69], v[162:165]
	v_mfma_f32_16x16x32_bf16 v[66:69], v[62:65], v[70:73], v[66:69]
	v_mfma_f32_16x16x32_bf16 v[146:149], v[58:61], v[170:173], v[146:149]
	v_mfma_f32_16x16x32_bf16 v[146:149], v[62:65], v[174:177], v[146:149]
	v_mfma_f32_16x16x32_bf16 v[134:137], v[50:53], v[178:181], v[134:137]
	v_mfma_f32_16x16x32_bf16 v[134:137], v[54:57], v[208:211], v[134:137]
	v_mfma_f32_16x16x32_bf16 v[130:133], v[58:61], v[178:181], v[130:133]
	v_mfma_f32_16x16x32_bf16 v[130:133], v[62:65], v[208:211], v[130:133]
	v_mfma_f32_16x16x32_bf16 v[118:121], v[50:53], v[212:215], v[118:121]
	v_mfma_f32_16x16x32_bf16 v[118:121], v[54:57], v[216:219], v[118:121]
	v_mfma_f32_16x16x32_bf16 v[114:117], v[58:61], v[212:215], v[114:117]
	v_mfma_f32_16x16x32_bf16 v[114:117], v[62:65], v[216:219], v[114:117]
	v_mfma_f32_16x16x32_bf16 v[70:73], v[50:53], v[170:173], v[150:153]
	v_mfma_f32_16x16x32_bf16 v[70:73], v[54:57], v[174:177], v[70:73]
	s_barrier
	s_add_i32 vcc_lo, s96, s61
	s_mov_b32 m0, vcc_lo
	ds_read_b128 v[150:153], v239 offset:16384
	ds_read_b128 v[162:165], v239 offset:17408
	ds_read_b128 v[170:173], v239 offset:18432
	ds_read_b128 v[174:177], v239 offset:19456
	ds_read_b128 v[178:181], v239 offset:20480
	ds_read_b128 v[208:211], v239 offset:21504
	ds_read_b128 v[212:215], v239 offset:22528
	ds_read_b128 v[216:219], v239 offset:23552
	global_load_lds_dwordx4 v186, s[88:89]
	s_add_i32 m0, vcc_lo, 0x2000
	s_add_u32 vcc_lo, s88, 0x100000
	s_addc_u32 vcc_hi, s89, 0
	s_add_i32 s58, s70, s61
	global_load_lds_dwordx4 v190, s[88:89]
	s_mov_b32 m0, s58
	s_nop 0
	global_load_lds_dwordx4 v186, vcc
	s_add_i32 m0, s58, 0x2000
	s_nop 0
	global_load_lds_dwordx4 v190, vcc
	s_mov_b32 m0, s62
	s_nop 0
	global_load_lds_dwordx4 v184, s[90:91]
	s_mov_b32 m0, s63
	s_nop 0
	global_load_lds_dwordx4 v188, s[90:91]
	s_waitcnt vmcnt(8)
	s_waitcnt lgkmcnt(0)
	s_barrier
	v_mfma_f32_16x16x32_bf16 v[110:113], v[10:13], v[150:153], v[110:113]
	v_mfma_f32_16x16x32_bf16 v[110:113], v[14:17], v[162:165], v[110:113]
	v_mfma_f32_16x16x32_bf16 v[106:109], v[42:45], v[150:153], v[106:109]
	v_mfma_f32_16x16x32_bf16 v[106:109], v[46:49], v[162:165], v[106:109]
	v_mfma_f32_16x16x32_bf16 v[94:97], v[10:13], v[170:173], v[94:97]
	v_mfma_f32_16x16x32_bf16 v[94:97], v[14:17], v[174:177], v[94:97]
	v_mfma_f32_16x16x32_bf16 v[90:93], v[42:45], v[170:173], v[90:93]
	v_mfma_f32_16x16x32_bf16 v[90:93], v[46:49], v[174:177], v[90:93]
	v_mfma_f32_16x16x32_bf16 v[78:81], v[10:13], v[178:181], v[78:81]
	v_mfma_f32_16x16x32_bf16 v[78:81], v[14:17], v[208:211], v[78:81]
	v_mfma_f32_16x16x32_bf16 v[74:77], v[42:45], v[178:181], v[74:77]
	v_mfma_f32_16x16x32_bf16 v[74:77], v[46:49], v[208:211], v[74:77]
	v_mfma_f32_16x16x32_bf16 v[10:13], v[10:13], v[212:215], v[30:33]
	v_mfma_f32_16x16x32_bf16 v[10:13], v[14:17], v[216:219], v[10:13]
	v_mfma_f32_16x16x32_bf16 v[14:17], v[42:45], v[212:215], v[26:29]
	v_mfma_f32_16x16x32_bf16 v[14:17], v[46:49], v[216:219], v[14:17]
	v_mfma_f32_16x16x32_bf16 v[26:29], v[50:53], v[150:153], v[102:105]
	v_mfma_f32_16x16x32_bf16 v[42:45], v[54:57], v[162:165], v[26:29]
	v_mfma_f32_16x16x32_bf16 v[26:29], v[58:61], v[150:153], v[98:101]
	v_mfma_f32_16x16x32_bf16 v[46:49], v[62:65], v[162:165], v[26:29]
	v_mfma_f32_16x16x32_bf16 v[26:29], v[50:53], v[170:173], v[86:89]
	v_mfma_f32_16x16x32_bf16 v[86:89], v[54:57], v[174:177], v[26:29]
	v_mfma_f32_16x16x32_bf16 v[26:29], v[58:61], v[170:173], v[82:85]
	v_mfma_f32_16x16x32_bf16 v[82:85], v[62:65], v[174:177], v[26:29]
	v_mfma_f32_16x16x32_bf16 v[26:29], v[50:53], v[178:181], v[38:41]
	v_mfma_f32_16x16x32_bf16 v[38:41], v[54:57], v[208:211], v[26:29]
	v_mfma_f32_16x16x32_bf16 v[26:29], v[58:61], v[178:181], v[34:37]
	v_mfma_f32_16x16x32_bf16 v[34:37], v[62:65], v[208:211], v[26:29]
	v_mfma_f32_16x16x32_bf16 v[22:25], v[50:53], v[212:215], v[22:25]
	v_mfma_f32_16x16x32_bf16 v[22:25], v[54:57], v[216:219], v[22:25]
	v_mfma_f32_16x16x32_bf16 v[18:21], v[58:61], v[212:215], v[18:21]
	v_mfma_f32_16x16x32_bf16 v[18:21], v[62:65], v[216:219], v[18:21]
	s_barrier
; #define PG8_STAGE(bufoff, gbase, voff) do { _Pragma("unroll") for (int _i = 0; _i < 2; ++_i) \
;         __builtin_amdgcn_global_load_lds((const unsigned*)((const char*)(gbase) + (voff)[_i]), (PG8_LAS unsigned*)(lds + (bufoff) + ldsw + _i * 8192), 16, 0, 0); } while (0)
; #define PG8_LDA(dst, b, h) do { _Pragma("unroll") for (int m = 0; m < 4; ++m) _Pragma("unroll") for (int k = 0; k < 2; ++k) dst[m][k] = *(const PG8_LAS bf16x8*)(lds + PG8_SA(b, h) + aoff + m * 2048 + k * 1024); } while (0)
; #define PG8_LDB(dst, b, h) do { _Pragma("unroll") for (int n = 0; n < 2; ++n) _Pragma("unroll") for (int k = 0; k < 2; ++k) dst[n][k] = *(const PG8_LAS bf16x8*)(lds + PG8_SB(b, h) + boff + n * 2048 + k * 1024); } while (0)
; #define PG8_MMA(ai, bj, At, Bt) do { __builtin_amdgcn_s_setprio(1); _Pragma("unroll") for (int m = 0; m < 4; ++m) _Pragma("unroll") for (int n = 0; n < 2; ++n) _Pragma("unroll") for (int k = 0; k < 2; ++k) \
;         acc[ai][bj][m][n] = __builtin_amdgcn_mfma_f32_16x16x32_bf16(Bt[n][k], At[m][k], acc[ai][bj][m][n], 0, 0, 0); __builtin_amdgcn_s_setprio(0); } while (0)
; #define PG8_WAIT_V(n) asm volatile("s_waitcnt vmcnt(" #n ")" ::: "memory")
; #define PG8_WAIT_L(n) asm volatile("s_waitcnt lgkmcnt(" #n ")" ::: "memory")
; #define PG8_BAR __builtin_amdgcn_s_barrier()
; #define PG8_SCHED __builtin_amdgcn_sched_barrier(0)
; template <class Epi, class Sched, bool ALIGN_EPI = false, bool SP2 = false>
; __device__ __forceinline__ void gemm_phase(PG8_LAS unsigned char* lds, const Gemm g, const Sched& S, const Epi& E) {
;     ...
;             PG8_LDB(B0, 1, 0); PG8_LDB(B1, 1, 1); PG8_SCHED; PG8_LDA(At, 1, 0); PG8_STAGE(PG8_SA(0, 1), a2 + hstep, voffA);
;             PG8_WAIT_V(8); PG8_WAIT_L(0); PG8_BAR; PG8_MMA(0, 0, At, B0); PG8_MMA(0, 1, At, B1); PG8_BAR; PG8_SCHED;
;             PG8_LDA(At, 1, 1); PG8_STAGE(PG8_SB(1, 0), b3, voffB); PG8_STAGE(PG8_SB(1, 1), b3 + hstep, voffB); PG8_STAGE(PG8_SA(1, 0), a3, voffA);
;             PG8_WAIT_V(8); PG8_WAIT_L(0); PG8_BAR; PG8_MMA(1, 0, At, B0); PG8_MMA(1, 1, At, B1); PG8_BAR; PG8_SCHED;
	s_add_i32 s58, 0, 0x18000
	s_add_i32 s59, 0, 0x1c000
	v_add_u32_e32 v54, s58, v1
	v_add_u32_e32 v98, s59, v1
	ds_read_b128 v[26:29], v54
	ds_read_b128 v[30:33], v54 offset:1024
	ds_read_b128 v[50:53], v54 offset:2048
	ds_read_b128 v[54:57], v54 offset:3072
	ds_read_b128 v[58:61], v98
	ds_read_b128 v[62:65], v98 offset:1024
	ds_read_b128 v[170:173], v98 offset:2048
	ds_read_b128 v[174:177], v98 offset:3072
	s_add_u32 s90, s90, 0x100000
	s_addc_u32 s91, s91, 0
	s_mov_b32 m0, s73
	ds_read_b128 v[98:101], v239 offset:32768
	ds_read_b128 v[102:105], v239 offset:33792
	ds_read_b128 v[178:181], v239 offset:34816
	ds_read_b128 v[208:211], v239 offset:35840
	ds_read_b128 v[212:215], v239 offset:36864
	ds_read_b128 v[216:219], v239 offset:37888
	ds_read_b128 v[220:223], v239 offset:38912
	ds_read_b128 v[224:227], v239 offset:39936
	global_load_lds_dwordx4 v184, s[90:91]
	s_mov_b32 m0, s75
	s_nop 0
	global_load_lds_dwordx4 v188, s[90:91]
	s_waitcnt vmcnt(8)
	s_waitcnt lgkmcnt(0)
	s_barrier
	v_mfma_f32_16x16x32_bf16 v[150:153], v[26:29], v[178:181], v[158:161]
	v_mfma_f32_16x16x32_bf16 v[158:161], v[30:33], v[208:211], v[150:153]
	v_mfma_f32_16x16x32_bf16 v[6:9], v[26:29], v[98:101], v[6:9]
	v_mfma_f32_16x16x32_bf16 v[6:9], v[30:33], v[102:105], v[6:9]
	v_mfma_f32_16x16x32_bf16 v[2:5], v[50:53], v[98:101], v[2:5]
	v_mfma_f32_16x16x32_bf16 v[2:5], v[54:57], v[102:105], v[2:5]
	v_mfma_f32_16x16x32_bf16 v[150:153], v[50:53], v[178:181], v[154:157]
	v_mfma_f32_16x16x32_bf16 v[154:157], v[54:57], v[208:211], v[150:153]
	v_mfma_f32_16x16x32_bf16 v[142:145], v[26:29], v[212:215], v[142:145]
	v_mfma_f32_16x16x32_bf16 v[142:145], v[30:33], v[216:219], v[142:145]
	v_mfma_f32_16x16x32_bf16 v[138:141], v[50:53], v[212:215], v[138:141]
	v_mfma_f32_16x16x32_bf16 v[138:141], v[54:57], v[216:219], v[138:141]
	v_mfma_f32_16x16x32_bf16 v[126:129], v[26:29], v[220:223], v[126:129]
	v_mfma_f32_16x16x32_bf16 v[126:129], v[30:33], v[224:227], v[126:129]
	v_mfma_f32_16x16x32_bf16 v[122:125], v[50:53], v[220:223], v[122:125]
	v_mfma_f32_16x16x32_bf16 v[122:125], v[54:57], v[224:227], v[122:125]
	v_mfma_f32_16x16x32_bf16 v[66:69], v[170:173], v[98:101], v[66:69]
	v_mfma_f32_16x16x32_bf16 v[162:165], v[174:177], v[102:105], v[66:69]
	v_mfma_f32_16x16x32_bf16 v[150:153], v[58:61], v[98:101], v[166:169]
	v_mfma_f32_16x16x32_bf16 v[166:169], v[62:65], v[102:105], v[150:153]
	v_mfma_f32_16x16x32_bf16 v[66:69], v[58:61], v[178:181], v[70:73]
	v_mfma_f32_16x16x32_bf16 v[150:153], v[62:65], v[208:211], v[66:69]
	v_mfma_f32_16x16x32_bf16 v[66:69], v[170:173], v[178:181], v[146:149]
	v_mfma_f32_16x16x32_bf16 v[146:149], v[174:177], v[208:211], v[66:69]
	v_mfma_f32_16x16x32_bf16 v[66:69], v[58:61], v[212:215], v[134:137]
	v_mfma_f32_16x16x32_bf16 v[134:137], v[62:65], v[216:219], v[66:69]
	v_mfma_f32_16x16x32_bf16 v[66:69], v[170:173], v[212:215], v[130:133]
	v_mfma_f32_16x16x32_bf16 v[130:133], v[174:177], v[216:219], v[66:69]
	v_mfma_f32_16x16x32_bf16 v[66:69], v[58:61], v[220:223], v[118:121]
	v_mfma_f32_16x16x32_bf16 v[118:121], v[62:65], v[224:227], v[66:69]
	v_mfma_f32_16x16x32_bf16 v[66:69], v[170:173], v[220:223], v[114:117]
	v_mfma_f32_16x16x32_bf16 v[114:117], v[174:177], v[224:227], v[66:69]
	s_barrier
	s_add_i32 s58, s58, s61
	s_add_u32 s100, s88, 0x80
	s_addc_u32 s101, s89, 0
	s_mov_b32 m0, s58
	s_nop 1
	ds_read_b128 v[66:69], v239 offset:49152
	ds_read_b128 v[70:73], v239 offset:50176
	ds_read_b128 v[178:181], v239 offset:51200
	ds_read_b128 v[208:211], v239 offset:52224
	ds_read_b128 v[212:215], v239 offset:53248
	ds_read_b128 v[216:219], v239 offset:54272
	ds_read_b128 v[220:223], v239 offset:55296
	ds_read_b128 v[224:227], v239 offset:56320
	global_load_lds_dwordx4 v186, s[100:101]
	s_add_i32 m0, s58, 0x2000
	s_add_i32 s58, s59, s61
	global_load_lds_dwordx4 v190, s[100:101]
	s_add_u32 s88, s88, 0x100080
	s_addc_u32 s89, s89, 0
	s_add_u32 s100, s90, 0xfff00080
	s_addc_u32 s101, s91, -1
	s_mov_b32 m0, s58
	s_nop 0
	global_load_lds_dwordx4 v186, s[88:89]
	s_add_i32 m0, s58, 0x2000
	s_nop 0
	global_load_lds_dwordx4 v190, s[88:89]
	s_mov_b32 m0, s29
	s_nop 0
	global_load_lds_dwordx4 v184, s[100:101]
	s_mov_b32 m0, s95
	s_nop 0
	global_load_lds_dwordx4 v188, s[100:101]
	s_waitcnt vmcnt(8)
	s_waitcnt lgkmcnt(0)
	s_barrier
	v_mfma_f32_16x16x32_bf16 v[98:101], v[26:29], v[66:69], v[110:113]
	v_mfma_f32_16x16x32_bf16 v[110:113], v[30:33], v[70:73], v[98:101]
	v_mfma_f32_16x16x32_bf16 v[94:97], v[26:29], v[178:181], v[94:97]
	v_mfma_f32_16x16x32_bf16 v[94:97], v[30:33], v[208:211], v[94:97]
	v_mfma_f32_16x16x32_bf16 v[78:81], v[26:29], v[212:215], v[78:81]
	v_mfma_f32_16x16x32_bf16 v[78:81], v[30:33], v[216:219], v[78:81]
	v_mfma_f32_16x16x32_bf16 v[10:13], v[26:29], v[220:223], v[10:13]
	v_mfma_f32_16x16x32_bf16 v[30:33], v[30:33], v[224:227], v[10:13]
	v_mfma_f32_16x16x32_bf16 v[98:101], v[50:53], v[66:69], v[106:109]
	v_mfma_f32_16x16x32_bf16 v[106:109], v[54:57], v[70:73], v[98:101]
	v_mfma_f32_16x16x32_bf16 v[90:93], v[50:53], v[178:181], v[90:93]
	v_mfma_f32_16x16x32_bf16 v[90:93], v[54:57], v[208:211], v[90:93]
	v_mfma_f32_16x16x32_bf16 v[74:77], v[50:53], v[212:215], v[74:77]
	v_mfma_f32_16x16x32_bf16 v[74:77], v[54:57], v[216:219], v[74:77]
	v_mfma_f32_16x16x32_bf16 v[10:13], v[50:53], v[220:223], v[14:17]
	v_mfma_f32_16x16x32_bf16 v[26:29], v[54:57], v[224:227], v[10:13]
	v_mfma_f32_16x16x32_bf16 v[10:13], v[58:61], v[66:69], v[42:45]
	v_mfma_f32_16x16x32_bf16 v[102:105], v[62:65], v[70:73], v[10:13]
	v_mfma_f32_16x16x32_bf16 v[10:13], v[170:173], v[66:69], v[46:49]
	v_mfma_f32_16x16x32_bf16 v[98:101], v[174:177], v[70:73], v[10:13]
	v_mfma_f32_16x16x32_bf16 v[10:13], v[58:61], v[178:181], v[86:89]
	v_mfma_f32_16x16x32_bf16 v[86:89], v[62:65], v[208:211], v[10:13]
	v_mfma_f32_16x16x32_bf16 v[10:13], v[170:173], v[178:181], v[82:85]
	v_mfma_f32_16x16x32_bf16 v[82:85], v[174:177], v[208:211], v[10:13]
	v_mfma_f32_16x16x32_bf16 v[10:13], v[58:61], v[212:215], v[38:41]
	v_mfma_f32_16x16x32_bf16 v[38:41], v[62:65], v[216:219], v[10:13]
	v_mfma_f32_16x16x32_bf16 v[10:13], v[170:173], v[212:215], v[34:37]
	v_mfma_f32_16x16x32_bf16 v[34:37], v[174:177], v[216:219], v[10:13]
	v_mfma_f32_16x16x32_bf16 v[10:13], v[58:61], v[220:223], v[22:25]
	v_mfma_f32_16x16x32_bf16 v[22:25], v[62:65], v[224:227], v[10:13]
	v_mfma_f32_16x16x32_bf16 v[10:13], v[170:173], v[220:223], v[18:21]
	v_mfma_f32_16x16x32_bf16 v[18:21], v[174:177], v[224:227], v[10:13]
	s_barrier
	s_add_i32 s93, s93, 2
	s_add_u32 s86, s86, 0x100
	s_addc_u32 s87, s87, 0
	s_add_u32 s85, s85, 0x100
	s_addc_u32 s92, s92, 0
	s_cmp_gt_u32 s93, 61
	s_cbranch_scc0 .LBB0_2650
	s_and_b64 vcc, exec, s[42:43]
	s_cbranch_vccz .LBB0_2653
	s_barrier

; #define PG8_STAGE(bufoff, gbase, voff) do { _Pragma("unroll") for (int _i = 0; _i < 2; ++_i) \
;         __builtin_amdgcn_global_load_lds((const unsigned*)((const char*)(gbase) + (voff)[_i]), (PG8_LAS unsigned*)(lds + (bufoff) + ldsw + _i * 8192), 16, 0, 0); } while (0)
; #define PG8_LDA(dst, b, h) do { _Pragma("unroll") for (int m = 0; m < 4; ++m) _Pragma("unroll") for (int k = 0; k < 2; ++k) dst[m][k] = *(const PG8_LAS bf16x8*)(lds + PG8_SA(b, h) + aoff + m * 2048 + k * 1024); } while (0)
; #define PG8_LDB(dst, b, h) do { _Pragma("unroll") for (int n = 0; n < 2; ++n) _Pragma("unroll") for (int k = 0; k < 2; ++k) dst[n][k] = *(const PG8_LAS bf16x8*)(lds + PG8_SB(b, h) + boff + n * 2048 + k * 1024); } while (0)
; #define PG8_MMA(ai, bj, At, Bt) do { __builtin_amdgcn_s_setprio(1); _Pragma("unroll") for (int m = 0; m < 4; ++m) _Pragma("unroll") for (int n = 0; n < 2; ++n) _Pragma("unroll") for (int k = 0; k < 2; ++k) \
;         acc[ai][bj][m][n] = __builtin_amdgcn_mfma_f32_16x16x32_bf16(Bt[n][k], At[m][k], acc[ai][bj][m][n], 0, 0, 0); __builtin_amdgcn_s_setprio(0); } while (0)
; #define PG8_WAIT_V(n) asm volatile("s_waitcnt vmcnt(" #n ")" ::: "memory")
; #define PG8_WAIT_L(n) asm volatile("s_waitcnt lgkmcnt(" #n ")" ::: "memory")
; #define PG8_BAR __builtin_amdgcn_s_barrier()
; #define PG8_SCHED __builtin_amdgcn_sched_barrier(0)
; template <class Epi, class Sched, bool ALIGN_EPI = false, bool SP2 = false>
; __device__ __forceinline__ void gemm_phase(PG8_LAS unsigned char* lds, const Gemm g, const Sched& S, const Epi& E) {
;     ...
;             PG8_LDB(B0, 0, 0); PG8_LDB(B1, 0, 1); PG8_SCHED; PG8_LDA(At, 0, 0); PG8_STAGE(PG8_SA(1, 1), a1 + hstep, voffA);
;             PG8_WAIT_V(8); PG8_WAIT_L(0); PG8_BAR; PG8_MMA(0, 0, At, B0); PG8_MMA(0, 1, At, B1); PG8_BAR; PG8_SCHED;
;             PG8_LDA(At, 0, 1); PG8_STAGE(PG8_SB(0, 0), b2, voffB); PG8_STAGE(PG8_SB(0, 1), b2 + hstep, voffB); PG8_STAGE(PG8_SA(0, 0), a2, voffA);
;             PG8_WAIT_V(8); PG8_WAIT_L(0); PG8_BAR; PG8_MMA(1, 0, At, B0); PG8_MMA(1, 1, At, B1); PG8_BAR; PG8_SCHED;
.LBB0_3522:
	ds_read_b128 v[144:147], v177
	ds_read_b128 v[148:151], v177 offset:1024
	ds_read_b128 v[152:155], v177 offset:2048
	ds_read_b128 v[156:159], v177 offset:3072
	ds_read_b128 v[160:163], v178
	ds_read_b128 v[164:167], v178 offset:1024
	ds_read_b128 v[168:171], v178 offset:2048
	ds_read_b128 v[172:175], v178 offset:3072
	s_add_u32 s40, s38, 0x100
	s_addc_u32 s41, s39, 0
	s_cmp_eq_u32 s69, s71
	s_cselect_b32 s45, s35, s41
	s_cselect_b32 s44, s34, s40
	s_cselect_b32 s43, s37, s70
	s_cselect_b32 s42, s36, s31
	s_add_i32 m0, s51, 0xc000
	ds_read_b128 v[180:183], v179
	ds_read_b128 v[184:187], v179 offset:1024
	ds_read_b128 v[188:191], v179 offset:2048
	ds_read_b128 v[192:195], v179 offset:3072
	ds_read_b128 v[196:199], v179 offset:4096
	ds_read_b128 v[200:203], v179 offset:5120
	ds_read_b128 v[204:207], v179 offset:6144
	ds_read_b128 v[208:211], v179 offset:7168
	global_load_lds_dwordx4 v138, s[38:39]
	s_add_i32 m0, s51, 0xe000
	s_nop 0
	global_load_lds_dwordx4 v140, s[38:39]
	s_waitcnt vmcnt(8)
	s_waitcnt lgkmcnt(0)
	s_barrier
	v_mfma_f32_16x16x32_bf16 v[126:129], v[144:147], v[180:183], v[126:129]
	v_mfma_f32_16x16x32_bf16 v[126:129], v[148:151], v[184:187], v[126:129]
	v_mfma_f32_16x16x32_bf16 v[122:125], v[152:155], v[180:183], v[122:125]
	v_mfma_f32_16x16x32_bf16 v[122:125], v[156:159], v[184:187], v[122:125]
	v_mfma_f32_16x16x32_bf16 v[110:113], v[144:147], v[188:191], v[110:113]
	v_mfma_f32_16x16x32_bf16 v[110:113], v[148:151], v[192:195], v[110:113]
	v_mfma_f32_16x16x32_bf16 v[106:109], v[152:155], v[188:191], v[106:109]
	v_mfma_f32_16x16x32_bf16 v[106:109], v[156:159], v[192:195], v[106:109]
	v_mfma_f32_16x16x32_bf16 v[94:97], v[144:147], v[196:199], v[94:97]
	v_mfma_f32_16x16x32_bf16 v[94:97], v[148:151], v[200:203], v[94:97]
	v_mfma_f32_16x16x32_bf16 v[90:93], v[152:155], v[196:199], v[90:93]
	v_mfma_f32_16x16x32_bf16 v[90:93], v[156:159], v[200:203], v[90:93]
	v_mfma_f32_16x16x32_bf16 v[78:81], v[144:147], v[204:207], v[78:81]
	v_mfma_f32_16x16x32_bf16 v[78:81], v[148:151], v[208:211], v[78:81]
	v_mfma_f32_16x16x32_bf16 v[74:77], v[152:155], v[204:207], v[74:77]
	v_mfma_f32_16x16x32_bf16 v[74:77], v[156:159], v[208:211], v[74:77]
	v_mfma_f32_16x16x32_bf16 v[118:121], v[160:163], v[180:183], v[118:121]
	v_mfma_f32_16x16x32_bf16 v[118:121], v[164:167], v[184:187], v[118:121]
	v_mfma_f32_16x16x32_bf16 v[114:117], v[168:171], v[180:183], v[114:117]
	v_mfma_f32_16x16x32_bf16 v[114:117], v[172:175], v[184:187], v[114:117]
	v_mfma_f32_16x16x32_bf16 v[102:105], v[160:163], v[188:191], v[102:105]
	v_mfma_f32_16x16x32_bf16 v[102:105], v[164:167], v[192:195], v[102:105]
	v_mfma_f32_16x16x32_bf16 v[98:101], v[168:171], v[188:191], v[98:101]
	v_mfma_f32_16x16x32_bf16 v[98:101], v[172:175], v[192:195], v[98:101]
	v_mfma_f32_16x16x32_bf16 v[86:89], v[160:163], v[196:199], v[86:89]
	v_mfma_f32_16x16x32_bf16 v[86:89], v[164:167], v[200:203], v[86:89]
	v_mfma_f32_16x16x32_bf16 v[82:85], v[168:171], v[196:199], v[82:85]
	v_mfma_f32_16x16x32_bf16 v[82:85], v[172:175], v[200:203], v[82:85]
	v_mfma_f32_16x16x32_bf16 v[70:73], v[160:163], v[204:207], v[70:73]
	v_mfma_f32_16x16x32_bf16 v[70:73], v[164:167], v[208:211], v[70:73]
	v_mfma_f32_16x16x32_bf16 v[66:69], v[168:171], v[204:207], v[66:69]
	v_mfma_f32_16x16x32_bf16 v[66:69], v[172:175], v[208:211], v[66:69]
	s_barrier
	s_add_i32 s38, s63, s50
	s_mov_b32 m0, s38
	ds_read_b128 v[180:183], v179 offset:16384
	ds_read_b128 v[184:187], v179 offset:17408
	ds_read_b128 v[188:191], v179 offset:18432
	ds_read_b128 v[192:195], v179 offset:19456
	ds_read_b128 v[196:199], v179 offset:20480
	ds_read_b128 v[200:203], v179 offset:21504
	ds_read_b128 v[204:207], v179 offset:22528
	ds_read_b128 v[208:211], v179 offset:23552
	global_load_lds_dwordx4 v130, s[42:43]
	s_add_i32 m0, s38, 0x2000
	s_add_u32 s38, s42, 0x300000
	s_addc_u32 s39, s43, 0
	s_add_i32 s58, s64, s50
	global_load_lds_dwordx4 v132, s[42:43]
	s_mov_b32 m0, s58
	s_nop 0
	global_load_lds_dwordx4 v130, s[38:39]
	s_add_i32 m0, s58, 0x2000
	s_nop 0
	global_load_lds_dwordx4 v132, s[38:39]
	s_mov_b32 m0, s51
	s_nop 0
	global_load_lds_dwordx4 v130, s[44:45]
	s_mov_b32 m0, s52
	s_nop 0
	global_load_lds_dwordx4 v132, s[44:45]
	s_waitcnt vmcnt(8)
	s_waitcnt lgkmcnt(0)
	s_barrier
	v_mfma_f32_16x16x32_bf16 v[62:65], v[144:147], v[180:183], v[62:65]
	v_mfma_f32_16x16x32_bf16 v[62:65], v[148:151], v[184:187], v[62:65]
	v_mfma_f32_16x16x32_bf16 v[58:61], v[152:155], v[180:183], v[58:61]
	v_mfma_f32_16x16x32_bf16 v[58:61], v[156:159], v[184:187], v[58:61]
	v_mfma_f32_16x16x32_bf16 v[46:49], v[144:147], v[188:191], v[46:49]
	v_mfma_f32_16x16x32_bf16 v[46:49], v[148:151], v[192:195], v[46:49]
	v_mfma_f32_16x16x32_bf16 v[42:45], v[152:155], v[188:191], v[42:45]
	v_mfma_f32_16x16x32_bf16 v[42:45], v[156:159], v[192:195], v[42:45]
	v_mfma_f32_16x16x32_bf16 v[30:33], v[144:147], v[196:199], v[30:33]
	v_mfma_f32_16x16x32_bf16 v[30:33], v[148:151], v[200:203], v[30:33]
	v_mfma_f32_16x16x32_bf16 v[26:29], v[152:155], v[196:199], v[26:29]
	v_mfma_f32_16x16x32_bf16 v[26:29], v[156:159], v[200:203], v[26:29]
	v_mfma_f32_16x16x32_bf16 v[14:17], v[144:147], v[204:207], v[14:17]
	v_mfma_f32_16x16x32_bf16 v[14:17], v[148:151], v[208:211], v[14:17]
	v_mfma_f32_16x16x32_bf16 v[10:13], v[152:155], v[204:207], v[10:13]
	v_mfma_f32_16x16x32_bf16 v[10:13], v[156:159], v[208:211], v[10:13]
	v_mfma_f32_16x16x32_bf16 v[54:57], v[160:163], v[180:183], v[54:57]
	v_mfma_f32_16x16x32_bf16 v[54:57], v[164:167], v[184:187], v[54:57]
	v_mfma_f32_16x16x32_bf16 v[50:53], v[168:171], v[180:183], v[50:53]
	v_mfma_f32_16x16x32_bf16 v[50:53], v[172:175], v[184:187], v[50:53]
	v_mfma_f32_16x16x32_bf16 v[38:41], v[160:163], v[188:191], v[38:41]
	v_mfma_f32_16x16x32_bf16 v[38:41], v[164:167], v[192:195], v[38:41]
	v_mfma_f32_16x16x32_bf16 v[34:37], v[168:171], v[188:191], v[34:37]
	v_mfma_f32_16x16x32_bf16 v[34:37], v[172:175], v[192:195], v[34:37]
	v_mfma_f32_16x16x32_bf16 v[22:25], v[160:163], v[196:199], v[22:25]
	v_mfma_f32_16x16x32_bf16 v[22:25], v[164:167], v[200:203], v[22:25]
	v_mfma_f32_16x16x32_bf16 v[18:21], v[168:171], v[196:199], v[18:21]
	v_mfma_f32_16x16x32_bf16 v[18:21], v[172:175], v[200:203], v[18:21]
	v_mfma_f32_16x16x32_bf16 v[6:9], v[160:163], v[204:207], v[6:9]
	v_mfma_f32_16x16x32_bf16 v[6:9], v[164:167], v[208:211], v[6:9]
	v_mfma_f32_16x16x32_bf16 v[2:5], v[168:171], v[204:207], v[2:5]
	v_mfma_f32_16x16x32_bf16 v[2:5], v[172:175], v[208:211], v[2:5]
	s_barrier
; #define PG8_STAGE(bufoff, gbase, voff) do { _Pragma("unroll") for (int _i = 0; _i < 2; ++_i) \
;         __builtin_amdgcn_global_load_lds((const unsigned*)((const char*)(gbase) + (voff)[_i]), (PG8_LAS unsigned*)(lds + (bufoff) + ldsw + _i * 8192), 16, 0, 0); } while (0)
; #define PG8_LDA(dst, b, h) do { _Pragma("unroll") for (int m = 0; m < 4; ++m) _Pragma("unroll") for (int k = 0; k < 2; ++k) dst[m][k] = *(const PG8_LAS bf16x8*)(lds + PG8_SA(b, h) + aoff + m * 2048 + k * 1024); } while (0)
; #define PG8_LDB(dst, b, h) do { _Pragma("unroll") for (int n = 0; n < 2; ++n) _Pragma("unroll") for (int k = 0; k < 2; ++k) dst[n][k] = *(const PG8_LAS bf16x8*)(lds + PG8_SB(b, h) + boff + n * 2048 + k * 1024); } while (0)
; #define PG8_MMA(ai, bj, At, Bt) do { __builtin_amdgcn_s_setprio(1); _Pragma("unroll") for (int m = 0; m < 4; ++m) _Pragma("unroll") for (int n = 0; n < 2; ++n) _Pragma("unroll") for (int k = 0; k < 2; ++k) \
;         acc[ai][bj][m][n] = __builtin_amdgcn_mfma_f32_16x16x32_bf16(Bt[n][k], At[m][k], acc[ai][bj][m][n], 0, 0, 0); __builtin_amdgcn_s_setprio(0); } while (0)
; #define PG8_WAIT_V(n) asm volatile("s_waitcnt vmcnt(" #n ")" ::: "memory")
; #define PG8_WAIT_L(n) asm volatile("s_waitcnt lgkmcnt(" #n ")" ::: "memory")
; #define PG8_BAR __builtin_amdgcn_s_barrier()
; #define PG8_SCHED __builtin_amdgcn_sched_barrier(0)
;     __device__ __forceinline__ void operator()(const f32x4 (&acc)[2][2][4][2], const Unit& u, int wr, int wc, int fr, int fq) const {
;     ...
;         if (u.ntu != 192) {
; template <class Epi, class Sched, bool ALIGN_EPI = false, bool SP2 = false>
; __device__ __forceinline__ void gemm_phase(PG8_LAS unsigned char* lds, const Gemm g, const Sched& S, const Epi& E) {
;     ...
;             PG8_LDB(B0, 1, 0); PG8_LDB(B1, 1, 1); PG8_SCHED; PG8_LDA(At, 1, 0); PG8_STAGE(PG8_SA(0, 1), a2 + hstep, voffA);
;             PG8_WAIT_V(8); PG8_WAIT_L(0); PG8_BAR; PG8_MMA(0, 0, At, B0); PG8_MMA(0, 1, At, B1); PG8_BAR; PG8_SCHED;
;             PG8_LDA(At, 1, 1); PG8_STAGE(PG8_SB(1, 0), b3, voffB); PG8_STAGE(PG8_SB(1, 1), b3 + hstep, voffB); PG8_STAGE(PG8_SA(1, 0), a3, voffA);
;             PG8_WAIT_V(8); PG8_WAIT_L(0); PG8_BAR; PG8_MMA(1, 0, At, B0); PG8_MMA(1, 1, At, B1); PG8_BAR; PG8_SCHED;
	s_add_i32 s58, 0, 0x18000
	v_add_u32_e32 v134, s58, v1
	s_add_i32 s59, 0, 0x1c000
	ds_read_b128 v[144:147], v134
	ds_read_b128 v[148:151], v134 offset:1024
	ds_read_b128 v[152:155], v134 offset:2048
	ds_read_b128 v[156:159], v134 offset:3072
	v_add_u32_e32 v134, s59, v1
	ds_read_b128 v[160:163], v134
	ds_read_b128 v[164:167], v134 offset:1024
	ds_read_b128 v[168:171], v134 offset:2048
	ds_read_b128 v[172:175], v134 offset:3072
	s_add_u32 s38, s44, 0x300000
	s_addc_u32 s39, s45, 0
	s_mov_b32 m0, s53
	ds_read_b128 v[180:183], v179 offset:32768
	ds_read_b128 v[184:187], v179 offset:33792
	ds_read_b128 v[188:191], v179 offset:34816
	ds_read_b128 v[192:195], v179 offset:35840
	ds_read_b128 v[196:199], v179 offset:36864
	ds_read_b128 v[200:203], v179 offset:37888
	ds_read_b128 v[204:207], v179 offset:38912
	ds_read_b128 v[208:211], v179 offset:39936
	global_load_lds_dwordx4 v130, s[38:39]
	s_mov_b32 m0, s54
	s_nop 0
	global_load_lds_dwordx4 v132, s[38:39]
	s_waitcnt vmcnt(8)
	s_waitcnt lgkmcnt(0)
	s_barrier
	v_mfma_f32_16x16x32_bf16 v[126:129], v[144:147], v[180:183], v[126:129]
	v_mfma_f32_16x16x32_bf16 v[126:129], v[148:151], v[184:187], v[126:129]
	v_mfma_f32_16x16x32_bf16 v[122:125], v[152:155], v[180:183], v[122:125]
	v_mfma_f32_16x16x32_bf16 v[122:125], v[156:159], v[184:187], v[122:125]
	v_mfma_f32_16x16x32_bf16 v[110:113], v[144:147], v[188:191], v[110:113]
	v_mfma_f32_16x16x32_bf16 v[110:113], v[148:151], v[192:195], v[110:113]
	v_mfma_f32_16x16x32_bf16 v[106:109], v[152:155], v[188:191], v[106:109]
	v_mfma_f32_16x16x32_bf16 v[106:109], v[156:159], v[192:195], v[106:109]
	v_mfma_f32_16x16x32_bf16 v[94:97], v[144:147], v[196:199], v[94:97]
	v_mfma_f32_16x16x32_bf16 v[94:97], v[148:151], v[200:203], v[94:97]
	v_mfma_f32_16x16x32_bf16 v[90:93], v[152:155], v[196:199], v[90:93]
	v_mfma_f32_16x16x32_bf16 v[90:93], v[156:159], v[200:203], v[90:93]
	v_mfma_f32_16x16x32_bf16 v[78:81], v[144:147], v[204:207], v[78:81]
	v_mfma_f32_16x16x32_bf16 v[78:81], v[148:151], v[208:211], v[78:81]
	v_mfma_f32_16x16x32_bf16 v[74:77], v[152:155], v[204:207], v[74:77]
	v_mfma_f32_16x16x32_bf16 v[74:77], v[156:159], v[208:211], v[74:77]
	v_mfma_f32_16x16x32_bf16 v[118:121], v[160:163], v[180:183], v[118:121]
	v_mfma_f32_16x16x32_bf16 v[118:121], v[164:167], v[184:187], v[118:121]
	v_mfma_f32_16x16x32_bf16 v[114:117], v[168:171], v[180:183], v[114:117]
	v_mfma_f32_16x16x32_bf16 v[114:117], v[172:175], v[184:187], v[114:117]
	v_mfma_f32_16x16x32_bf16 v[102:105], v[160:163], v[188:191], v[102:105]
	v_mfma_f32_16x16x32_bf16 v[102:105], v[164:167], v[192:195], v[102:105]
	v_mfma_f32_16x16x32_bf16 v[98:101], v[168:171], v[188:191], v[98:101]
	v_mfma_f32_16x16x32_bf16 v[98:101], v[172:175], v[192:195], v[98:101]
	v_mfma_f32_16x16x32_bf16 v[86:89], v[160:163], v[196:199], v[86:89]
	v_mfma_f32_16x16x32_bf16 v[86:89], v[164:167], v[200:203], v[86:89]
	v_mfma_f32_16x16x32_bf16 v[82:85], v[168:171], v[196:199], v[82:85]
	v_mfma_f32_16x16x32_bf16 v[82:85], v[172:175], v[200:203], v[82:85]
	v_mfma_f32_16x16x32_bf16 v[70:73], v[160:163], v[204:207], v[70:73]
	v_mfma_f32_16x16x32_bf16 v[70:73], v[164:167], v[208:211], v[70:73]
	v_mfma_f32_16x16x32_bf16 v[66:69], v[168:171], v[204:207], v[66:69]
	v_mfma_f32_16x16x32_bf16 v[66:69], v[172:175], v[208:211], v[66:69]
	s_barrier
	s_add_i32 s38, s58, s50
	s_add_u32 s98, s42, 0x80
	s_addc_u32 s99, s43, 0
	s_add_u32 s100, s44, 0x80
	s_addc_u32 s101, s45, 0
	s_mov_b32 m0, s38
	ds_read_b128 v[180:183], v179 offset:49152
	ds_read_b128 v[184:187], v179 offset:50176
	ds_read_b128 v[188:191], v179 offset:51200
	ds_read_b128 v[192:195], v179 offset:52224
	ds_read_b128 v[196:199], v179 offset:53248
	ds_read_b128 v[200:203], v179 offset:54272
	ds_read_b128 v[204:207], v179 offset:55296
	ds_read_b128 v[208:211], v179 offset:56320
	global_load_lds_dwordx4 v130, s[98:99]
	s_add_i32 m0, s38, 0x2000
	s_add_u32 s38, s42, 0x300080
	s_addc_u32 s39, s43, 0
	s_add_i32 s42, s59, s50
	global_load_lds_dwordx4 v132, s[98:99]
	s_mov_b32 m0, s42
	s_nop 0
	global_load_lds_dwordx4 v130, s[38:39]
	s_add_i32 m0, s42, 0x2000
	s_nop 0
	global_load_lds_dwordx4 v132, s[38:39]
	s_mov_b32 m0, s57
	s_nop 0
	global_load_lds_dwordx4 v130, s[100:101]
	s_mov_b32 m0, s60
	s_nop 0
	global_load_lds_dwordx4 v132, s[100:101]
	s_waitcnt vmcnt(8)
	s_waitcnt lgkmcnt(0)
	s_barrier
	v_mfma_f32_16x16x32_bf16 v[62:65], v[144:147], v[180:183], v[62:65]
	v_mfma_f32_16x16x32_bf16 v[62:65], v[148:151], v[184:187], v[62:65]
	v_mfma_f32_16x16x32_bf16 v[58:61], v[152:155], v[180:183], v[58:61]
	v_mfma_f32_16x16x32_bf16 v[58:61], v[156:159], v[184:187], v[58:61]
	v_mfma_f32_16x16x32_bf16 v[46:49], v[144:147], v[188:191], v[46:49]
	v_mfma_f32_16x16x32_bf16 v[46:49], v[148:151], v[192:195], v[46:49]
	v_mfma_f32_16x16x32_bf16 v[42:45], v[152:155], v[188:191], v[42:45]
	v_mfma_f32_16x16x32_bf16 v[42:45], v[156:159], v[192:195], v[42:45]
	v_mfma_f32_16x16x32_bf16 v[30:33], v[144:147], v[196:199], v[30:33]
	v_mfma_f32_16x16x32_bf16 v[30:33], v[148:151], v[200:203], v[30:33]
	v_mfma_f32_16x16x32_bf16 v[26:29], v[152:155], v[196:199], v[26:29]
	v_mfma_f32_16x16x32_bf16 v[26:29], v[156:159], v[200:203], v[26:29]
	v_mfma_f32_16x16x32_bf16 v[14:17], v[144:147], v[204:207], v[14:17]
	v_mfma_f32_16x16x32_bf16 v[14:17], v[148:151], v[208:211], v[14:17]
	v_mfma_f32_16x16x32_bf16 v[10:13], v[152:155], v[204:207], v[10:13]
	v_mfma_f32_16x16x32_bf16 v[10:13], v[156:159], v[208:211], v[10:13]
	v_mfma_f32_16x16x32_bf16 v[54:57], v[160:163], v[180:183], v[54:57]
	v_mfma_f32_16x16x32_bf16 v[54:57], v[164:167], v[184:187], v[54:57]
	v_mfma_f32_16x16x32_bf16 v[50:53], v[168:171], v[180:183], v[50:53]
	v_mfma_f32_16x16x32_bf16 v[50:53], v[172:175], v[184:187], v[50:53]
	v_mfma_f32_16x16x32_bf16 v[38:41], v[160:163], v[188:191], v[38:41]
	v_mfma_f32_16x16x32_bf16 v[38:41], v[164:167], v[192:195], v[38:41]
	v_mfma_f32_16x16x32_bf16 v[34:37], v[168:171], v[188:191], v[34:37]
	v_mfma_f32_16x16x32_bf16 v[34:37], v[172:175], v[192:195], v[34:37]
	v_mfma_f32_16x16x32_bf16 v[22:25], v[160:163], v[196:199], v[22:25]
	v_mfma_f32_16x16x32_bf16 v[22:25], v[164:167], v[200:203], v[22:25]
	v_mfma_f32_16x16x32_bf16 v[18:21], v[168:171], v[196:199], v[18:21]
	v_mfma_f32_16x16x32_bf16 v[18:21], v[172:175], v[200:203], v[18:21]
	v_mfma_f32_16x16x32_bf16 v[6:9], v[160:163], v[204:207], v[6:9]
	v_mfma_f32_16x16x32_bf16 v[6:9], v[164:167], v[208:211], v[6:9]
	v_mfma_f32_16x16x32_bf16 v[2:5], v[168:171], v[204:207], v[2:5]
	v_mfma_f32_16x16x32_bf16 v[2:5], v[172:175], v[208:211], v[2:5]
	s_barrier
	s_add_i32 s42, s71, 2
	s_add_u32 s31, s31, 0x100
	s_addc_u32 s70, s70, 0
	s_cmp_ge_i32 s71, s69
	s_mov_b64 s[38:39], s[40:41]
	s_mov_b32 s71, s42
	s_cbranch_scc0 .LBB0_3522
	s_and_b64 vcc, exec, s[20:21]
	s_cbranch_vccz .LBB0_3543
	s_barrier
	v_lshl_or_b32 v144, s5, 8, v176
	s_cmpk_eq_i32 s69, 0xc0
	s_mov_b64 s[38:39], -1
	s_cbranch_scc0 .LBB0_3544
